# s_setprio 1 hoisted above the K-loop phase barrier (20 sites), on top of merged waits
# speedup vs baseline: 1.0072x; 1.0032x over previous
; #define PG8_STAGE(bufoff, gbase, voff) do { _Pragma("unroll") for (int _i = 0; _i < 2; ++_i) \
;         __builtin_amdgcn_global_load_lds((const unsigned*)((const char*)(gbase) + (voff)[_i]), (PG8_LAS unsigned*)(lds + (bufoff) + ldsw + _i * 8192), 16, 0, 0); } while (0)
; #define PG8_LDA(dst, b, h) do { _Pragma("unroll") for (int m = 0; m < 4; ++m) _Pragma("unroll") for (int k = 0; k < 2; ++k) dst[m][k] = *(const PG8_LAS bf16x8*)(lds + PG8_SA(b, h) + aoff + m * 2048 + k * 1024); } while (0)
; #define PG8_LDB(dst, b, h) do { _Pragma("unroll") for (int n = 0; n < 2; ++n) _Pragma("unroll") for (int k = 0; k < 2; ++k) dst[n][k] = *(const PG8_LAS bf16x8*)(lds + PG8_SB(b, h) + boff + n * 2048 + k * 1024); } while (0)
; #define PG8_MMA(ai, bj, At, Bt) do { __builtin_amdgcn_s_setprio(1); _Pragma("unroll") for (int m = 0; m < 4; ++m) _Pragma("unroll") for (int n = 0; n < 2; ++n) _Pragma("unroll") for (int k = 0; k < 2; ++k) \
;         acc[ai][bj][m][n] = __builtin_amdgcn_mfma_f32_16x16x32_bf16(Bt[n][k], At[m][k], acc[ai][bj][m][n], 0, 0, 0); __builtin_amdgcn_s_setprio(0); } while (0)
; #define PG8_WAIT_V(n) asm volatile("s_waitcnt vmcnt(" #n ")" ::: "memory")
; #define PG8_WAIT_L(n) asm volatile("s_waitcnt lgkmcnt(" #n ")" ::: "memory")
; #define PG8_BAR __builtin_amdgcn_s_barrier()
; #define PG8_SCHED __builtin_amdgcn_sched_barrier(0)
; template <class Epi, class Sched, bool ALIGN_EPI = false, bool SP2 = false>
; __device__ __forceinline__ void gemm_phase(PG8_LAS unsigned char* lds, const Gemm g, const Sched& S, const Epi& E) {
;     ...
;             PG8_LDB(B0, 0, 0); PG8_LDB(B1, 0, 1); PG8_SCHED; PG8_LDA(At, 0, 0); PG8_STAGE(PG8_SA(1, 1), a1 + hstepA, voffA);
;             PG8_WAIT_V(8); PG8_WAIT_L(0); PG8_BAR; PG8_MMA(0, 0, At, B0); PG8_MMA(0, 1, At, B1); PG8_BAR; PG8_SCHED;
;             PG8_LDA(At, 0, 1); PG8_STAGE(PG8_SB(0, 0), b2, voffB); PG8_STAGE(PG8_SB(0, 1), b2 + hstepB, voffB); PG8_STAGE(PG8_SA(0, 0), a2, voffA);
;             PG8_WAIT_V(8); PG8_WAIT_L(0); PG8_BAR; PG8_MMA(1, 0, At, B0); PG8_MMA(1, 1, At, B1); PG8_BAR; PG8_SCHED;
.LBB0_157:
	v_add_u32_e32 v136, s2, v139
	ds_read_b128 v[186:189], v136
	ds_read_b128 v[190:193], v136 offset:1024
	ds_read_b128 v[194:197], v136 offset:2048
	ds_read_b128 v[198:201], v136 offset:3072
	v_add_u32_e32 v136, s3, v139
	ds_read_b128 v[202:205], v136
	ds_read_b128 v[206:209], v136 offset:1024
	ds_read_b128 v[210:213], v136 offset:2048
	ds_read_b128 v[214:217], v136 offset:3072
	s_add_u32 s38, s36, 0xfffc0080
	s_addc_u32 s39, s37, -1
	s_cmp_eq_u32 s45, 12
	s_cselect_b32 s41, s7, s39
	s_cselect_b32 s40, s29, s38
	s_cselect_b32 s39, s27, s44
	s_cselect_b32 s38, s42, s43
	v_lshl_add_u64 v[250:251], s[36:37], 0, v[178:179]
	s_add_i32 m0, s63, 0xc000
	ds_read_b128 v[218:221], v159
	ds_read_b128 v[222:225], v159 offset:1024
	ds_read_b128 v[226:229], v159 offset:2048
	ds_read_b128 v[230:233], v159 offset:3072
	ds_read_b128 v[234:237], v159 offset:4096
	ds_read_b128 v[238:241], v159 offset:5120
	ds_read_b128 v[242:245], v159 offset:6144
	ds_read_b128 v[246:249], v159 offset:7168
	global_load_lds_dwordx4 v[250:251], off
	v_lshl_add_u64 v[250:251], s[36:37], 0, v[180:181]
	s_add_i32 m0, s63, 0xe000
	s_nop 0
	global_load_lds_dwordx4 v[250:251], off
	s_waitcnt vmcnt(8) lgkmcnt(0)
	s_setprio 1
	s_barrier
	v_mfma_f32_16x16x32_bf16 v[124:127], v[186:189], v[218:221], v[124:127]
	v_mfma_f32_16x16x32_bf16 v[120:123], v[194:197], v[218:221], v[120:123]
	v_mfma_f32_16x16x32_bf16 v[108:111], v[186:189], v[226:229], v[108:111]
	v_mfma_f32_16x16x32_bf16 v[104:107], v[194:197], v[226:229], v[104:107]
	v_mfma_f32_16x16x32_bf16 v[92:95], v[186:189], v[234:237], v[92:95]
	v_mfma_f32_16x16x32_bf16 v[88:91], v[194:197], v[234:237], v[88:91]
	v_mfma_f32_16x16x32_bf16 v[76:79], v[186:189], v[242:245], v[76:79]
	v_mfma_f32_16x16x32_bf16 v[72:75], v[194:197], v[242:245], v[72:75]
	v_mfma_f32_16x16x32_bf16 v[124:127], v[190:193], v[222:225], v[124:127]
	v_mfma_f32_16x16x32_bf16 v[120:123], v[198:201], v[222:225], v[120:123]
	v_mfma_f32_16x16x32_bf16 v[108:111], v[190:193], v[230:233], v[108:111]
	v_mfma_f32_16x16x32_bf16 v[104:107], v[198:201], v[230:233], v[104:107]
	v_mfma_f32_16x16x32_bf16 v[92:95], v[190:193], v[238:241], v[92:95]
	v_mfma_f32_16x16x32_bf16 v[88:91], v[198:201], v[238:241], v[88:91]
	v_mfma_f32_16x16x32_bf16 v[76:79], v[190:193], v[246:249], v[76:79]
	v_mfma_f32_16x16x32_bf16 v[72:75], v[198:201], v[246:249], v[72:75]
	v_mfma_f32_16x16x32_bf16 v[116:119], v[202:205], v[218:221], v[116:119]
	v_mfma_f32_16x16x32_bf16 v[112:115], v[210:213], v[218:221], v[112:115]
	v_mfma_f32_16x16x32_bf16 v[100:103], v[202:205], v[226:229], v[100:103]
	v_mfma_f32_16x16x32_bf16 v[96:99], v[210:213], v[226:229], v[96:99]
	v_mfma_f32_16x16x32_bf16 v[84:87], v[202:205], v[234:237], v[84:87]
	v_mfma_f32_16x16x32_bf16 v[80:83], v[210:213], v[234:237], v[80:83]
	v_mfma_f32_16x16x32_bf16 v[68:71], v[202:205], v[242:245], v[68:71]
	v_mfma_f32_16x16x32_bf16 v[64:67], v[210:213], v[242:245], v[64:67]
	v_mfma_f32_16x16x32_bf16 v[116:119], v[206:209], v[222:225], v[116:119]
	v_mfma_f32_16x16x32_bf16 v[112:115], v[214:217], v[222:225], v[112:115]
	v_mfma_f32_16x16x32_bf16 v[100:103], v[206:209], v[230:233], v[100:103]
	v_mfma_f32_16x16x32_bf16 v[96:99], v[214:217], v[230:233], v[96:99]
	v_mfma_f32_16x16x32_bf16 v[84:87], v[206:209], v[238:241], v[84:87]
	v_mfma_f32_16x16x32_bf16 v[80:83], v[214:217], v[238:241], v[80:83]
	v_mfma_f32_16x16x32_bf16 v[68:71], v[206:209], v[246:249], v[68:71]
	v_mfma_f32_16x16x32_bf16 v[64:67], v[214:217], v[246:249], v[64:67]
	s_setprio 0
	s_barrier
	s_add_i32 s46, s2, s62
	v_lshl_add_u64 v[250:251], s[38:39], 0, v[130:131]
	s_mov_b32 m0, s46
	ds_read_b128 v[218:221], v159 offset:16384
	ds_read_b128 v[222:225], v159 offset:17408
	ds_read_b128 v[226:229], v159 offset:18432
	ds_read_b128 v[230:233], v159 offset:19456
	ds_read_b128 v[234:237], v159 offset:20480
	ds_read_b128 v[238:241], v159 offset:21504
	ds_read_b128 v[242:245], v159 offset:22528
	ds_read_b128 v[246:249], v159 offset:23552
	global_load_lds_dwordx4 v[250:251], off
	s_add_i32 m0, s46, 0x2000
	s_add_u32 s46, s38, 0x40000
	v_lshl_add_u64 v[252:253], s[38:39], 0, v[134:135]
	s_addc_u32 s47, s39, 0
	s_add_i32 s48, s3, s62
	global_load_lds_dwordx4 v[252:253], off
	v_lshl_add_u64 v[166:167], s[46:47], 0, v[130:131]
	s_mov_b32 m0, s48
	v_lshl_add_u64 v[168:169], s[40:41], 0, v[132:133]
	global_load_lds_dwordx4 v[166:167], off
	v_lshl_add_u64 v[166:167], s[46:47], 0, v[134:135]
	s_add_i32 m0, s48, 0x2000
	s_nop 0
	global_load_lds_dwordx4 v[166:167], off
	v_lshl_add_u64 v[166:167], s[40:41], 0, v[128:129]
	s_mov_b32 m0, s63
	s_nop 0
	global_load_lds_dwordx4 v[166:167], off
	s_mov_b32 m0, s64
	s_nop 0
	global_load_lds_dwordx4 v[168:169], off
	s_waitcnt vmcnt(8) lgkmcnt(0)
	s_setprio 1
	s_barrier
; #define PG8_STAGE(bufoff, gbase, voff) do { _Pragma("unroll") for (int _i = 0; _i < 2; ++_i) \
;         __builtin_amdgcn_global_load_lds((const unsigned*)((const char*)(gbase) + (voff)[_i]), (PG8_LAS unsigned*)(lds + (bufoff) + ldsw + _i * 8192), 16, 0, 0); } while (0)
; #define PG8_LDA(dst, b, h) do { _Pragma("unroll") for (int m = 0; m < 4; ++m) _Pragma("unroll") for (int k = 0; k < 2; ++k) dst[m][k] = *(const PG8_LAS bf16x8*)(lds + PG8_SA(b, h) + aoff + m * 2048 + k * 1024); } while (0)
; #define PG8_LDB(dst, b, h) do { _Pragma("unroll") for (int n = 0; n < 2; ++n) _Pragma("unroll") for (int k = 0; k < 2; ++k) dst[n][k] = *(const PG8_LAS bf16x8*)(lds + PG8_SB(b, h) + boff + n * 2048 + k * 1024); } while (0)
; #define PG8_MMA(ai, bj, At, Bt) do { __builtin_amdgcn_s_setprio(1); _Pragma("unroll") for (int m = 0; m < 4; ++m) _Pragma("unroll") for (int n = 0; n < 2; ++n) _Pragma("unroll") for (int k = 0; k < 2; ++k) \
;         acc[ai][bj][m][n] = __builtin_amdgcn_mfma_f32_16x16x32_bf16(Bt[n][k], At[m][k], acc[ai][bj][m][n], 0, 0, 0); __builtin_amdgcn_s_setprio(0); } while (0)
; #define PG8_WAIT_V(n) asm volatile("s_waitcnt vmcnt(" #n ")" ::: "memory")
; #define PG8_WAIT_L(n) asm volatile("s_waitcnt lgkmcnt(" #n ")" ::: "memory")
; #define PG8_BAR __builtin_amdgcn_s_barrier()
; #define PG8_SCHED __builtin_amdgcn_sched_barrier(0)
; template <class Epi, class Sched, bool ALIGN_EPI = false, bool SP2 = false>
; __device__ __forceinline__ void gemm_phase(PG8_LAS unsigned char* lds, const Gemm g, const Sched& S, const Epi& E) {
;     ...
;             PG8_WAIT_V(8); PG8_WAIT_L(0); PG8_BAR; PG8_MMA(1, 0, At, B0); PG8_MMA(1, 1, At, B1); PG8_BAR; PG8_SCHED;
;             PG8_LDB(B0, 1, 0); PG8_LDB(B1, 1, 1); PG8_SCHED; PG8_LDA(At, 1, 0); PG8_STAGE(PG8_SA(0, 1), a2 + hstepA, voffA);
;             PG8_WAIT_V(8); PG8_WAIT_L(0); PG8_BAR; PG8_MMA(0, 0, At, B0); PG8_MMA(0, 1, At, B1); PG8_BAR; PG8_SCHED;
	v_mfma_f32_16x16x32_bf16 v[60:63], v[186:189], v[218:221], v[60:63]
	v_mfma_f32_16x16x32_bf16 v[56:59], v[194:197], v[218:221], v[56:59]
	v_mfma_f32_16x16x32_bf16 v[44:47], v[186:189], v[226:229], v[44:47]
	v_mfma_f32_16x16x32_bf16 v[40:43], v[194:197], v[226:229], v[40:43]
	v_mfma_f32_16x16x32_bf16 v[28:31], v[186:189], v[234:237], v[28:31]
	v_mfma_f32_16x16x32_bf16 v[24:27], v[194:197], v[234:237], v[24:27]
	v_mfma_f32_16x16x32_bf16 v[12:15], v[186:189], v[242:245], v[12:15]
	v_mfma_f32_16x16x32_bf16 v[8:11], v[194:197], v[242:245], v[8:11]
	v_mfma_f32_16x16x32_bf16 v[60:63], v[190:193], v[222:225], v[60:63]
	v_mfma_f32_16x16x32_bf16 v[56:59], v[198:201], v[222:225], v[56:59]
	v_mfma_f32_16x16x32_bf16 v[44:47], v[190:193], v[230:233], v[44:47]
	v_mfma_f32_16x16x32_bf16 v[40:43], v[198:201], v[230:233], v[40:43]
	v_mfma_f32_16x16x32_bf16 v[28:31], v[190:193], v[238:241], v[28:31]
	v_mfma_f32_16x16x32_bf16 v[24:27], v[198:201], v[238:241], v[24:27]
	v_mfma_f32_16x16x32_bf16 v[12:15], v[190:193], v[246:249], v[12:15]
	v_mfma_f32_16x16x32_bf16 v[8:11], v[198:201], v[246:249], v[8:11]
	v_mfma_f32_16x16x32_bf16 v[52:55], v[202:205], v[218:221], v[52:55]
	v_mfma_f32_16x16x32_bf16 v[48:51], v[210:213], v[218:221], v[48:51]
	v_mfma_f32_16x16x32_bf16 v[36:39], v[202:205], v[226:229], v[36:39]
	v_mfma_f32_16x16x32_bf16 v[32:35], v[210:213], v[226:229], v[32:35]
	v_mfma_f32_16x16x32_bf16 v[20:23], v[202:205], v[234:237], v[20:23]
	v_mfma_f32_16x16x32_bf16 v[16:19], v[210:213], v[234:237], v[16:19]
	v_mfma_f32_16x16x32_bf16 v[4:7], v[202:205], v[242:245], v[4:7]
	v_mfma_f32_16x16x32_bf16 v[0:3], v[210:213], v[242:245], v[0:3]
	v_mfma_f32_16x16x32_bf16 v[52:55], v[206:209], v[222:225], v[52:55]
	v_mfma_f32_16x16x32_bf16 v[48:51], v[214:217], v[222:225], v[48:51]
	v_mfma_f32_16x16x32_bf16 v[36:39], v[206:209], v[230:233], v[36:39]
	v_mfma_f32_16x16x32_bf16 v[32:35], v[214:217], v[230:233], v[32:35]
	v_mfma_f32_16x16x32_bf16 v[20:23], v[206:209], v[238:241], v[20:23]
	v_mfma_f32_16x16x32_bf16 v[16:19], v[214:217], v[238:241], v[16:19]
	v_mfma_f32_16x16x32_bf16 v[4:7], v[206:209], v[246:249], v[4:7]
	v_mfma_f32_16x16x32_bf16 v[0:3], v[214:217], v[246:249], v[0:3]
	s_setprio 0
	s_barrier
	s_add_i32 s46, 0, 0x18000
	v_add_u32_e32 v136, s46, v139
	s_add_i32 s47, 0, 0x1c000
	ds_read_b128 v[186:189], v136
	ds_read_b128 v[190:193], v136 offset:1024
	ds_read_b128 v[194:197], v136 offset:2048
	ds_read_b128 v[198:201], v136 offset:3072
	v_add_u32_e32 v136, s47, v139
	ds_read_b128 v[202:205], v136
	ds_read_b128 v[206:209], v136 offset:1024
	ds_read_b128 v[210:213], v136 offset:2048
	ds_read_b128 v[214:217], v136 offset:3072
	s_add_u32 s40, s40, 0x40000
	s_addc_u32 s41, s41, 0
	s_mov_b32 m0, s65
	v_lshl_add_u64 v[170:171], s[40:41], 0, v[128:129]
	ds_read_b128 v[218:221], v159 offset:32768
	ds_read_b128 v[222:225], v159 offset:33792
	ds_read_b128 v[226:229], v159 offset:34816
	ds_read_b128 v[230:233], v159 offset:35840
	ds_read_b128 v[234:237], v159 offset:36864
	ds_read_b128 v[238:241], v159 offset:37888
	ds_read_b128 v[242:245], v159 offset:38912
	ds_read_b128 v[246:249], v159 offset:39936
	global_load_lds_dwordx4 v[170:171], off
	v_lshl_add_u64 v[170:171], s[40:41], 0, v[132:133]
	s_mov_b32 m0, s66
	s_nop 0
	global_load_lds_dwordx4 v[170:171], off
	s_waitcnt vmcnt(8) lgkmcnt(0)
	s_setprio 1
	s_barrier
	v_mfma_f32_16x16x32_bf16 v[124:127], v[186:189], v[218:221], v[124:127]
	v_mfma_f32_16x16x32_bf16 v[120:123], v[194:197], v[218:221], v[120:123]
	v_mfma_f32_16x16x32_bf16 v[108:111], v[186:189], v[226:229], v[108:111]
	v_mfma_f32_16x16x32_bf16 v[104:107], v[194:197], v[226:229], v[104:107]
	v_mfma_f32_16x16x32_bf16 v[92:95], v[186:189], v[234:237], v[92:95]
	v_mfma_f32_16x16x32_bf16 v[88:91], v[194:197], v[234:237], v[88:91]
	v_mfma_f32_16x16x32_bf16 v[76:79], v[186:189], v[242:245], v[76:79]
	v_mfma_f32_16x16x32_bf16 v[72:75], v[194:197], v[242:245], v[72:75]
	v_mfma_f32_16x16x32_bf16 v[124:127], v[190:193], v[222:225], v[124:127]
	v_mfma_f32_16x16x32_bf16 v[120:123], v[198:201], v[222:225], v[120:123]
	v_mfma_f32_16x16x32_bf16 v[108:111], v[190:193], v[230:233], v[108:111]
	v_mfma_f32_16x16x32_bf16 v[104:107], v[198:201], v[230:233], v[104:107]
	v_mfma_f32_16x16x32_bf16 v[92:95], v[190:193], v[238:241], v[92:95]
	v_mfma_f32_16x16x32_bf16 v[88:91], v[198:201], v[238:241], v[88:91]
	v_mfma_f32_16x16x32_bf16 v[76:79], v[190:193], v[246:249], v[76:79]
	v_mfma_f32_16x16x32_bf16 v[72:75], v[198:201], v[246:249], v[72:75]
	v_mfma_f32_16x16x32_bf16 v[116:119], v[202:205], v[218:221], v[116:119]
	v_mfma_f32_16x16x32_bf16 v[112:115], v[210:213], v[218:221], v[112:115]
	v_mfma_f32_16x16x32_bf16 v[100:103], v[202:205], v[226:229], v[100:103]
	v_mfma_f32_16x16x32_bf16 v[96:99], v[210:213], v[226:229], v[96:99]
	v_mfma_f32_16x16x32_bf16 v[84:87], v[202:205], v[234:237], v[84:87]
	v_mfma_f32_16x16x32_bf16 v[80:83], v[210:213], v[234:237], v[80:83]
	v_mfma_f32_16x16x32_bf16 v[68:71], v[202:205], v[242:245], v[68:71]
	v_mfma_f32_16x16x32_bf16 v[64:67], v[210:213], v[242:245], v[64:67]
	v_mfma_f32_16x16x32_bf16 v[116:119], v[206:209], v[222:225], v[116:119]
	v_mfma_f32_16x16x32_bf16 v[112:115], v[214:217], v[222:225], v[112:115]
	v_mfma_f32_16x16x32_bf16 v[100:103], v[206:209], v[230:233], v[100:103]
	v_mfma_f32_16x16x32_bf16 v[96:99], v[214:217], v[230:233], v[96:99]
	v_mfma_f32_16x16x32_bf16 v[84:87], v[206:209], v[238:241], v[84:87]
	v_mfma_f32_16x16x32_bf16 v[80:83], v[214:217], v[238:241], v[80:83]
	v_mfma_f32_16x16x32_bf16 v[68:71], v[206:209], v[246:249], v[68:71]
	v_mfma_f32_16x16x32_bf16 v[64:67], v[214:217], v[246:249], v[64:67]
	s_setprio 0
	s_barrier
; #define PG8_STAGE(bufoff, gbase, voff) do { _Pragma("unroll") for (int _i = 0; _i < 2; ++_i) \
;         __builtin_amdgcn_global_load_lds((const unsigned*)((const char*)(gbase) + (voff)[_i]), (PG8_LAS unsigned*)(lds + (bufoff) + ldsw + _i * 8192), 16, 0, 0); } while (0)
; #define PG8_LDA(dst, b, h) do { _Pragma("unroll") for (int m = 0; m < 4; ++m) _Pragma("unroll") for (int k = 0; k < 2; ++k) dst[m][k] = *(const PG8_LAS bf16x8*)(lds + PG8_SA(b, h) + aoff + m * 2048 + k * 1024); } while (0)
; #define PG8_MMA(ai, bj, At, Bt) do { __builtin_amdgcn_s_setprio(1); _Pragma("unroll") for (int m = 0; m < 4; ++m) _Pragma("unroll") for (int n = 0; n < 2; ++n) _Pragma("unroll") for (int k = 0; k < 2; ++k) \
;         acc[ai][bj][m][n] = __builtin_amdgcn_mfma_f32_16x16x32_bf16(Bt[n][k], At[m][k], acc[ai][bj][m][n], 0, 0, 0); __builtin_amdgcn_s_setprio(0); } while (0)
; #define PG8_WAIT_V(n) asm volatile("s_waitcnt vmcnt(" #n ")" ::: "memory")
; #define PG8_WAIT_L(n) asm volatile("s_waitcnt lgkmcnt(" #n ")" ::: "memory")
; #define PG8_BAR __builtin_amdgcn_s_barrier()
; #define PG8_SCHED __builtin_amdgcn_sched_barrier(0)
; template <class Epi, class Sched, bool ALIGN_EPI = false, bool SP2 = false>
; __device__ __forceinline__ void gemm_phase(PG8_LAS unsigned char* lds, const Gemm g, const Sched& S, const Epi& E) {
;     ...
;             PG8_LDA(At, 1, 1); PG8_STAGE(PG8_SB(1, 0), b3, voffB); PG8_STAGE(PG8_SB(1, 1), b3 + hstepB, voffB); PG8_STAGE(PG8_SA(1, 0), a3, voffA);
;             PG8_WAIT_V(8); PG8_WAIT_L(0); PG8_BAR; PG8_MMA(1, 0, At, B0); PG8_MMA(1, 1, At, B1); PG8_BAR; PG8_SCHED;
	s_add_i32 s40, s46, s62
	v_lshl_add_u64 v[170:171], v[250:251], 0, s[22:23]
	s_mov_b32 m0, s40
	ds_read_b128 v[218:221], v159 offset:49152
	ds_read_b128 v[222:225], v159 offset:50176
	ds_read_b128 v[226:229], v159 offset:51200
	ds_read_b128 v[230:233], v159 offset:52224
	ds_read_b128 v[234:237], v159 offset:53248
	ds_read_b128 v[238:241], v159 offset:54272
	ds_read_b128 v[242:245], v159 offset:55296
	ds_read_b128 v[246:249], v159 offset:56320
	global_load_lds_dwordx4 v[170:171], off
	s_add_i32 m0, s40, 0x2000
	s_add_u32 s38, s38, 0x40080
	v_lshl_add_u64 v[170:171], v[252:253], 0, s[22:23]
	s_addc_u32 s39, s39, 0
	s_add_i32 s40, s47, s62
	global_load_lds_dwordx4 v[170:171], off
	v_lshl_add_u64 v[170:171], s[38:39], 0, v[130:131]
	s_mov_b32 m0, s40
	v_lshl_add_u64 v[166:167], v[166:167], 0, s[22:23]
	global_load_lds_dwordx4 v[170:171], off
	v_lshl_add_u64 v[170:171], s[38:39], 0, v[134:135]
	s_add_i32 m0, s40, 0x2000
	s_nop 0
	global_load_lds_dwordx4 v[170:171], off
	s_mov_b32 m0, s93
	s_nop 0
	global_load_lds_dwordx4 v[166:167], off
	v_lshl_add_u64 v[166:167], v[168:169], 0, s[22:23]
	s_mov_b32 m0, s96
	s_nop 0
	global_load_lds_dwordx4 v[166:167], off
	s_waitcnt vmcnt(8) lgkmcnt(0)
	s_setprio 1
	s_barrier
	v_mfma_f32_16x16x32_bf16 v[60:63], v[186:189], v[218:221], v[60:63]
	v_mfma_f32_16x16x32_bf16 v[56:59], v[194:197], v[218:221], v[56:59]
	v_mfma_f32_16x16x32_bf16 v[44:47], v[186:189], v[226:229], v[44:47]
	v_mfma_f32_16x16x32_bf16 v[40:43], v[194:197], v[226:229], v[40:43]
	v_mfma_f32_16x16x32_bf16 v[28:31], v[186:189], v[234:237], v[28:31]
	v_mfma_f32_16x16x32_bf16 v[24:27], v[194:197], v[234:237], v[24:27]
	v_mfma_f32_16x16x32_bf16 v[12:15], v[186:189], v[242:245], v[12:15]
	v_mfma_f32_16x16x32_bf16 v[8:11], v[194:197], v[242:245], v[8:11]
	v_mfma_f32_16x16x32_bf16 v[60:63], v[190:193], v[222:225], v[60:63]
	v_mfma_f32_16x16x32_bf16 v[56:59], v[198:201], v[222:225], v[56:59]
	v_mfma_f32_16x16x32_bf16 v[44:47], v[190:193], v[230:233], v[44:47]
	v_mfma_f32_16x16x32_bf16 v[40:43], v[198:201], v[230:233], v[40:43]
	v_mfma_f32_16x16x32_bf16 v[28:31], v[190:193], v[238:241], v[28:31]
	v_mfma_f32_16x16x32_bf16 v[24:27], v[198:201], v[238:241], v[24:27]
	v_mfma_f32_16x16x32_bf16 v[12:15], v[190:193], v[246:249], v[12:15]
	v_mfma_f32_16x16x32_bf16 v[8:11], v[198:201], v[246:249], v[8:11]
	v_mfma_f32_16x16x32_bf16 v[52:55], v[202:205], v[218:221], v[52:55]
	v_mfma_f32_16x16x32_bf16 v[48:51], v[210:213], v[218:221], v[48:51]
	v_mfma_f32_16x16x32_bf16 v[36:39], v[202:205], v[226:229], v[36:39]
	v_mfma_f32_16x16x32_bf16 v[32:35], v[210:213], v[226:229], v[32:35]
	v_mfma_f32_16x16x32_bf16 v[20:23], v[202:205], v[234:237], v[20:23]
	v_mfma_f32_16x16x32_bf16 v[16:19], v[210:213], v[234:237], v[16:19]
	v_mfma_f32_16x16x32_bf16 v[4:7], v[202:205], v[242:245], v[4:7]
	v_mfma_f32_16x16x32_bf16 v[0:3], v[210:213], v[242:245], v[0:3]
	v_mfma_f32_16x16x32_bf16 v[52:55], v[206:209], v[222:225], v[52:55]
	v_mfma_f32_16x16x32_bf16 v[48:51], v[214:217], v[222:225], v[48:51]
	v_mfma_f32_16x16x32_bf16 v[36:39], v[206:209], v[230:233], v[36:39]
	v_mfma_f32_16x16x32_bf16 v[32:35], v[214:217], v[230:233], v[32:35]
	v_mfma_f32_16x16x32_bf16 v[20:23], v[206:209], v[238:241], v[20:23]
	v_mfma_f32_16x16x32_bf16 v[16:19], v[214:217], v[238:241], v[16:19]
	v_mfma_f32_16x16x32_bf16 v[4:7], v[206:209], v[246:249], v[4:7]
	v_mfma_f32_16x16x32_bf16 v[0:3], v[214:217], v[246:249], v[0:3]
	s_setprio 0
	s_barrier
	s_add_i32 s45, s45, 2
	s_add_u32 s36, s36, 0x100
	s_addc_u32 s37, s37, 0
	s_add_u32 s43, s43, 0x100
	s_addc_u32 s44, s44, 0
	s_cmp_gt_u32 s45, 13
	s_cbranch_scc0 .LBB0_157
	s_and_b64 vcc, exec, s[24:25]
	s_cbranch_vccz .LBB0_160
	s_barrier

; #define PG8_STAGE(bufoff, gbase, voff) do { _Pragma("unroll") for (int _i = 0; _i < 2; ++_i) \
;         __builtin_amdgcn_global_load_lds((const unsigned*)((const char*)(gbase) + (voff)[_i]), (PG8_LAS unsigned*)(lds + (bufoff) + ldsw + _i * 8192), 16, 0, 0); } while (0)
; #define PG8_LDA(dst, b, h) do { _Pragma("unroll") for (int m = 0; m < 4; ++m) _Pragma("unroll") for (int k = 0; k < 2; ++k) dst[m][k] = *(const PG8_LAS bf16x8*)(lds + PG8_SA(b, h) + aoff + m * 2048 + k * 1024); } while (0)
; #define PG8_LDB(dst, b, h) do { _Pragma("unroll") for (int n = 0; n < 2; ++n) _Pragma("unroll") for (int k = 0; k < 2; ++k) dst[n][k] = *(const PG8_LAS bf16x8*)(lds + PG8_SB(b, h) + boff + n * 2048 + k * 1024); } while (0)
; #define PG8_MMA(ai, bj, At, Bt) do { __builtin_amdgcn_s_setprio(1); _Pragma("unroll") for (int m = 0; m < 4; ++m) _Pragma("unroll") for (int n = 0; n < 2; ++n) _Pragma("unroll") for (int k = 0; k < 2; ++k) \
;         acc[ai][bj][m][n] = __builtin_amdgcn_mfma_f32_16x16x32_bf16(Bt[n][k], At[m][k], acc[ai][bj][m][n], 0, 0, 0); __builtin_amdgcn_s_setprio(0); } while (0)
; #define PG8_WAIT_V(n) asm volatile("s_waitcnt vmcnt(" #n ")" ::: "memory")
; #define PG8_WAIT_L(n) asm volatile("s_waitcnt lgkmcnt(" #n ")" ::: "memory")
; #define PG8_BAR __builtin_amdgcn_s_barrier()
; #define PG8_SCHED __builtin_amdgcn_sched_barrier(0)
; template <class Epi, class Sched, bool ALIGN_EPI = false, bool SP2 = false>
; __device__ __forceinline__ void gemm_phase(PG8_LAS unsigned char* lds, const Gemm g, const Sched& S, const Epi& E) {
;     ...
;             PG8_LDB(B0, 0, 0); PG8_LDB(B1, 0, 1); PG8_SCHED; PG8_LDA(At, 0, 0); PG8_STAGE(PG8_SA(1, 1), a1 + hstepA, voffA);
;             PG8_WAIT_V(8); PG8_WAIT_L(0); PG8_BAR; PG8_MMA(0, 0, At, B0); PG8_MMA(0, 1, At, B1); PG8_BAR; PG8_SCHED;
;             PG8_LDA(At, 0, 1); PG8_STAGE(PG8_SB(0, 0), b2, voffB); PG8_STAGE(PG8_SB(0, 1), b2 + hstepB, voffB); PG8_STAGE(PG8_SA(0, 0), a2, voffA);
;             PG8_WAIT_V(8); PG8_WAIT_L(0); PG8_BAR; PG8_MMA(1, 0, At, B0); PG8_MMA(1, 1, At, B1); PG8_BAR; PG8_SCHED;
.LBB0_470:
	ds_read_b128 v[158:161], v155
	ds_read_b128 v[162:165], v155 offset:1024
	ds_read_b128 v[166:169], v155 offset:2048
	ds_read_b128 v[170:173], v155 offset:3072
	ds_read_b128 v[174:177], v156
	ds_read_b128 v[178:181], v156 offset:1024
	ds_read_b128 v[186:189], v156 offset:2048
	ds_read_b128 v[190:193], v156 offset:3072
	s_add_u32 s12, s0, 0xfffc0080
	s_addc_u32 s13, s1, -1
	s_cmp_eq_u32 s44, 4
	s_cselect_b32 s17, s38, s13
	s_cselect_b32 s16, s39, s12
	s_cselect_b32 s13, s40, s43
	s_cselect_b32 s12, s41, s42
	v_lshl_add_u64 v[182:183], s[0:1], 0, v[140:141]
	s_add_i32 m0, s22, 0xc000
	ds_read_b128 v[194:197], v157
	ds_read_b128 v[198:201], v157 offset:1024
	ds_read_b128 v[202:205], v157 offset:2048
	ds_read_b128 v[206:209], v157 offset:3072
	ds_read_b128 v[210:213], v157 offset:4096
	ds_read_b128 v[214:217], v157 offset:5120
	ds_read_b128 v[218:221], v157 offset:6144
	ds_read_b128 v[222:225], v157 offset:7168
	global_load_lds_dwordx4 v[182:183], off
	v_lshl_add_u64 v[182:183], s[0:1], 0, v[142:143]
	s_add_i32 m0, s22, 0xe000
	s_nop 0
	global_load_lds_dwordx4 v[182:183], off
	s_waitcnt vmcnt(8) lgkmcnt(0)
	s_setprio 1
	s_barrier
	v_mfma_f32_16x16x32_bf16 v[124:127], v[158:161], v[194:197], v[124:127]
	v_mfma_f32_16x16x32_bf16 v[120:123], v[166:169], v[194:197], v[120:123]
	v_mfma_f32_16x16x32_bf16 v[116:119], v[158:161], v[202:205], v[116:119]
	v_mfma_f32_16x16x32_bf16 v[112:115], v[166:169], v[202:205], v[112:115]
	v_mfma_f32_16x16x32_bf16 v[108:111], v[158:161], v[210:213], v[108:111]
	v_mfma_f32_16x16x32_bf16 v[100:103], v[166:169], v[210:213], v[100:103]
	v_mfma_f32_16x16x32_bf16 v[92:95], v[158:161], v[218:221], v[92:95]
	v_mfma_f32_16x16x32_bf16 v[84:87], v[166:169], v[218:221], v[84:87]
	v_mfma_f32_16x16x32_bf16 v[124:127], v[162:165], v[198:201], v[124:127]
	v_mfma_f32_16x16x32_bf16 v[120:123], v[170:173], v[198:201], v[120:123]
	v_mfma_f32_16x16x32_bf16 v[116:119], v[162:165], v[206:209], v[116:119]
	v_mfma_f32_16x16x32_bf16 v[112:115], v[170:173], v[206:209], v[112:115]
	v_mfma_f32_16x16x32_bf16 v[108:111], v[162:165], v[214:217], v[108:111]
	v_mfma_f32_16x16x32_bf16 v[100:103], v[170:173], v[214:217], v[100:103]
	v_mfma_f32_16x16x32_bf16 v[92:95], v[162:165], v[222:225], v[92:95]
	v_mfma_f32_16x16x32_bf16 v[84:87], v[170:173], v[222:225], v[84:87]
	v_mfma_f32_16x16x32_bf16 v[104:107], v[174:177], v[194:197], v[104:107]
	v_mfma_f32_16x16x32_bf16 v[96:99], v[186:189], v[194:197], v[96:99]
	v_mfma_f32_16x16x32_bf16 v[88:91], v[174:177], v[202:205], v[88:91]
	v_mfma_f32_16x16x32_bf16 v[80:83], v[186:189], v[202:205], v[80:83]
	v_mfma_f32_16x16x32_bf16 v[76:79], v[174:177], v[210:213], v[76:79]
	v_mfma_f32_16x16x32_bf16 v[72:75], v[186:189], v[210:213], v[72:75]
	v_mfma_f32_16x16x32_bf16 v[68:71], v[174:177], v[218:221], v[68:71]
	v_mfma_f32_16x16x32_bf16 v[64:67], v[186:189], v[218:221], v[64:67]
	v_mfma_f32_16x16x32_bf16 v[104:107], v[178:181], v[198:201], v[104:107]
	v_mfma_f32_16x16x32_bf16 v[96:99], v[190:193], v[198:201], v[96:99]
	v_mfma_f32_16x16x32_bf16 v[88:91], v[178:181], v[206:209], v[88:91]
	v_mfma_f32_16x16x32_bf16 v[80:83], v[190:193], v[206:209], v[80:83]
	v_mfma_f32_16x16x32_bf16 v[76:79], v[178:181], v[214:217], v[76:79]
	v_mfma_f32_16x16x32_bf16 v[72:75], v[190:193], v[214:217], v[72:75]
	v_mfma_f32_16x16x32_bf16 v[68:71], v[178:181], v[222:225], v[68:71]
	v_mfma_f32_16x16x32_bf16 v[64:67], v[190:193], v[222:225], v[64:67]
	s_setprio 0
	s_barrier
	s_add_i32 s45, s33, s15
	v_lshl_add_u64 v[182:183], s[12:13], 0, v[132:133]
	s_mov_b32 m0, s45
	ds_read_b128 v[194:197], v157 offset:16384
	ds_read_b128 v[198:201], v157 offset:17408
	ds_read_b128 v[202:205], v157 offset:18432
	ds_read_b128 v[206:209], v157 offset:19456
	ds_read_b128 v[210:213], v157 offset:20480
	ds_read_b128 v[214:217], v157 offset:21504
	ds_read_b128 v[218:221], v157 offset:22528
	ds_read_b128 v[222:225], v157 offset:23552
	global_load_lds_dwordx4 v[182:183], off
	s_add_i32 m0, s45, 0x2000
	s_add_u32 s46, s12, 0x80000
	v_lshl_add_u64 v[226:227], s[12:13], 0, v[128:129]
	s_addc_u32 s47, s13, 0
	s_add_i32 s45, s34, s15
	global_load_lds_dwordx4 v[226:227], off
	v_lshl_add_u64 v[228:229], s[46:47], 0, v[132:133]
	s_mov_b32 m0, s45
	v_lshl_add_u64 v[230:231], s[16:17], 0, v[130:131]
	global_load_lds_dwordx4 v[228:229], off
	v_lshl_add_u64 v[228:229], s[46:47], 0, v[128:129]
	s_add_i32 m0, s45, 0x2000
	s_nop 0
	global_load_lds_dwordx4 v[228:229], off
	v_lshl_add_u64 v[228:229], s[16:17], 0, v[134:135]
	s_mov_b32 m0, s22
	s_nop 0
	global_load_lds_dwordx4 v[228:229], off
	s_mov_b32 m0, s25
	s_nop 0
	global_load_lds_dwordx4 v[230:231], off
	s_waitcnt vmcnt(8) lgkmcnt(0)
	s_setprio 1
	s_barrier
; #define PG8_STAGE(bufoff, gbase, voff) do { _Pragma("unroll") for (int _i = 0; _i < 2; ++_i) \
;         __builtin_amdgcn_global_load_lds((const unsigned*)((const char*)(gbase) + (voff)[_i]), (PG8_LAS unsigned*)(lds + (bufoff) + ldsw + _i * 8192), 16, 0, 0); } while (0)
; #define PG8_LDA(dst, b, h) do { _Pragma("unroll") for (int m = 0; m < 4; ++m) _Pragma("unroll") for (int k = 0; k < 2; ++k) dst[m][k] = *(const PG8_LAS bf16x8*)(lds + PG8_SA(b, h) + aoff + m * 2048 + k * 1024); } while (0)
; #define PG8_LDB(dst, b, h) do { _Pragma("unroll") for (int n = 0; n < 2; ++n) _Pragma("unroll") for (int k = 0; k < 2; ++k) dst[n][k] = *(const PG8_LAS bf16x8*)(lds + PG8_SB(b, h) + boff + n * 2048 + k * 1024); } while (0)
; #define PG8_MMA(ai, bj, At, Bt) do { __builtin_amdgcn_s_setprio(1); _Pragma("unroll") for (int m = 0; m < 4; ++m) _Pragma("unroll") for (int n = 0; n < 2; ++n) _Pragma("unroll") for (int k = 0; k < 2; ++k) \
;         acc[ai][bj][m][n] = __builtin_amdgcn_mfma_f32_16x16x32_bf16(Bt[n][k], At[m][k], acc[ai][bj][m][n], 0, 0, 0); __builtin_amdgcn_s_setprio(0); } while (0)
; #define PG8_WAIT_V(n) asm volatile("s_waitcnt vmcnt(" #n ")" ::: "memory")
; #define PG8_WAIT_L(n) asm volatile("s_waitcnt lgkmcnt(" #n ")" ::: "memory")
; #define PG8_BAR __builtin_amdgcn_s_barrier()
; #define PG8_SCHED __builtin_amdgcn_sched_barrier(0)
; template <class Epi, class Sched, bool ALIGN_EPI = false, bool SP2 = false>
; __device__ __forceinline__ void gemm_phase(PG8_LAS unsigned char* lds, const Gemm g, const Sched& S, const Epi& E) {
;     ...
;             PG8_WAIT_V(8); PG8_WAIT_L(0); PG8_BAR; PG8_MMA(1, 0, At, B0); PG8_MMA(1, 1, At, B1); PG8_BAR; PG8_SCHED;
;             PG8_LDB(B0, 1, 0); PG8_LDB(B1, 1, 1); PG8_SCHED; PG8_LDA(At, 1, 0); PG8_STAGE(PG8_SA(0, 1), a2 + hstepA, voffA);
;             PG8_WAIT_V(8); PG8_WAIT_L(0); PG8_BAR; PG8_MMA(0, 0, At, B0); PG8_MMA(0, 1, At, B1); PG8_BAR; PG8_SCHED;
	v_mfma_f32_16x16x32_bf16 v[60:63], v[158:161], v[194:197], v[60:63]
	v_mfma_f32_16x16x32_bf16 v[56:59], v[166:169], v[194:197], v[56:59]
	v_mfma_f32_16x16x32_bf16 v[52:55], v[158:161], v[202:205], v[52:55]
	v_mfma_f32_16x16x32_bf16 v[48:51], v[166:169], v[202:205], v[48:51]
	v_mfma_f32_16x16x32_bf16 v[44:47], v[158:161], v[210:213], v[44:47]
	v_mfma_f32_16x16x32_bf16 v[36:39], v[166:169], v[210:213], v[36:39]
	v_mfma_f32_16x16x32_bf16 v[28:31], v[158:161], v[218:221], v[28:31]
	v_mfma_f32_16x16x32_bf16 v[20:23], v[166:169], v[218:221], v[20:23]
	v_mfma_f32_16x16x32_bf16 v[60:63], v[162:165], v[198:201], v[60:63]
	v_mfma_f32_16x16x32_bf16 v[56:59], v[170:173], v[198:201], v[56:59]
	v_mfma_f32_16x16x32_bf16 v[52:55], v[162:165], v[206:209], v[52:55]
	v_mfma_f32_16x16x32_bf16 v[48:51], v[170:173], v[206:209], v[48:51]
	v_mfma_f32_16x16x32_bf16 v[44:47], v[162:165], v[214:217], v[44:47]
	v_mfma_f32_16x16x32_bf16 v[36:39], v[170:173], v[214:217], v[36:39]
	v_mfma_f32_16x16x32_bf16 v[28:31], v[162:165], v[222:225], v[28:31]
	v_mfma_f32_16x16x32_bf16 v[20:23], v[170:173], v[222:225], v[20:23]
	v_mfma_f32_16x16x32_bf16 v[40:43], v[174:177], v[194:197], v[40:43]
	v_mfma_f32_16x16x32_bf16 v[32:35], v[186:189], v[194:197], v[32:35]
	v_mfma_f32_16x16x32_bf16 v[24:27], v[174:177], v[202:205], v[24:27]
	v_mfma_f32_16x16x32_bf16 v[16:19], v[186:189], v[202:205], v[16:19]
	v_mfma_f32_16x16x32_bf16 v[12:15], v[174:177], v[210:213], v[12:15]
	v_mfma_f32_16x16x32_bf16 v[8:11], v[186:189], v[210:213], v[8:11]
	v_mfma_f32_16x16x32_bf16 v[4:7], v[174:177], v[218:221], v[4:7]
	v_mfma_f32_16x16x32_bf16 v[0:3], v[186:189], v[218:221], v[0:3]
	v_mfma_f32_16x16x32_bf16 v[40:43], v[178:181], v[198:201], v[40:43]
	v_mfma_f32_16x16x32_bf16 v[32:35], v[190:193], v[198:201], v[32:35]
	v_mfma_f32_16x16x32_bf16 v[24:27], v[178:181], v[206:209], v[24:27]
	v_mfma_f32_16x16x32_bf16 v[16:19], v[190:193], v[206:209], v[16:19]
	v_mfma_f32_16x16x32_bf16 v[12:15], v[178:181], v[214:217], v[12:15]
	v_mfma_f32_16x16x32_bf16 v[8:11], v[190:193], v[214:217], v[8:11]
	v_mfma_f32_16x16x32_bf16 v[4:7], v[178:181], v[222:225], v[4:7]
	v_mfma_f32_16x16x32_bf16 v[0:3], v[190:193], v[222:225], v[0:3]
	s_setprio 0
	s_barrier
	s_add_i32 s45, 0, 0x18000
	v_add_u32_e32 v136, s45, v150
	s_add_i32 s46, 0, 0x1c000
	ds_read_b128 v[158:161], v136
	ds_read_b128 v[162:165], v136 offset:1024
	ds_read_b128 v[166:169], v136 offset:2048
	ds_read_b128 v[170:173], v136 offset:3072
	v_add_u32_e32 v136, s46, v150
	ds_read_b128 v[174:177], v136
	ds_read_b128 v[178:181], v136 offset:1024
	ds_read_b128 v[186:189], v136 offset:2048
	ds_read_b128 v[190:193], v136 offset:3072
	s_add_u32 s16, s16, 0x40000
	s_addc_u32 s17, s17, 0
	s_mov_b32 m0, s26
	v_lshl_add_u64 v[232:233], s[16:17], 0, v[134:135]
	ds_read_b128 v[194:197], v157 offset:32768
	ds_read_b128 v[198:201], v157 offset:33792
	ds_read_b128 v[202:205], v157 offset:34816
	ds_read_b128 v[206:209], v157 offset:35840
	ds_read_b128 v[210:213], v157 offset:36864
	ds_read_b128 v[214:217], v157 offset:37888
	ds_read_b128 v[218:221], v157 offset:38912
	ds_read_b128 v[222:225], v157 offset:39936
	global_load_lds_dwordx4 v[232:233], off
	v_lshl_add_u64 v[232:233], s[16:17], 0, v[130:131]
	s_mov_b32 m0, s27
	s_nop 0
	global_load_lds_dwordx4 v[232:233], off
	s_waitcnt vmcnt(8) lgkmcnt(0)
	s_setprio 1
	s_barrier
	v_mfma_f32_16x16x32_bf16 v[124:127], v[158:161], v[194:197], v[124:127]
	v_mfma_f32_16x16x32_bf16 v[120:123], v[166:169], v[194:197], v[120:123]
	v_mfma_f32_16x16x32_bf16 v[116:119], v[158:161], v[202:205], v[116:119]
	v_mfma_f32_16x16x32_bf16 v[112:115], v[166:169], v[202:205], v[112:115]
	v_mfma_f32_16x16x32_bf16 v[108:111], v[158:161], v[210:213], v[108:111]
	v_mfma_f32_16x16x32_bf16 v[100:103], v[166:169], v[210:213], v[100:103]
	v_mfma_f32_16x16x32_bf16 v[92:95], v[158:161], v[218:221], v[92:95]
	v_mfma_f32_16x16x32_bf16 v[84:87], v[166:169], v[218:221], v[84:87]
	v_mfma_f32_16x16x32_bf16 v[124:127], v[162:165], v[198:201], v[124:127]
	v_mfma_f32_16x16x32_bf16 v[120:123], v[170:173], v[198:201], v[120:123]
	v_mfma_f32_16x16x32_bf16 v[116:119], v[162:165], v[206:209], v[116:119]
	v_mfma_f32_16x16x32_bf16 v[112:115], v[170:173], v[206:209], v[112:115]
	v_mfma_f32_16x16x32_bf16 v[108:111], v[162:165], v[214:217], v[108:111]
	v_mfma_f32_16x16x32_bf16 v[100:103], v[170:173], v[214:217], v[100:103]
	v_mfma_f32_16x16x32_bf16 v[92:95], v[162:165], v[222:225], v[92:95]
	v_mfma_f32_16x16x32_bf16 v[84:87], v[170:173], v[222:225], v[84:87]
	v_mfma_f32_16x16x32_bf16 v[104:107], v[174:177], v[194:197], v[104:107]
	v_mfma_f32_16x16x32_bf16 v[96:99], v[186:189], v[194:197], v[96:99]
	v_mfma_f32_16x16x32_bf16 v[88:91], v[174:177], v[202:205], v[88:91]
	v_mfma_f32_16x16x32_bf16 v[80:83], v[186:189], v[202:205], v[80:83]
	v_mfma_f32_16x16x32_bf16 v[76:79], v[174:177], v[210:213], v[76:79]
	v_mfma_f32_16x16x32_bf16 v[72:75], v[186:189], v[210:213], v[72:75]
	v_mfma_f32_16x16x32_bf16 v[68:71], v[174:177], v[218:221], v[68:71]
	v_mfma_f32_16x16x32_bf16 v[64:67], v[186:189], v[218:221], v[64:67]
	v_mfma_f32_16x16x32_bf16 v[104:107], v[178:181], v[198:201], v[104:107]
	v_mfma_f32_16x16x32_bf16 v[96:99], v[190:193], v[198:201], v[96:99]
	v_mfma_f32_16x16x32_bf16 v[88:91], v[178:181], v[206:209], v[88:91]
	v_mfma_f32_16x16x32_bf16 v[80:83], v[190:193], v[206:209], v[80:83]
	v_mfma_f32_16x16x32_bf16 v[76:79], v[178:181], v[214:217], v[76:79]
	v_mfma_f32_16x16x32_bf16 v[72:75], v[190:193], v[214:217], v[72:75]
	v_mfma_f32_16x16x32_bf16 v[68:71], v[178:181], v[222:225], v[68:71]
	v_mfma_f32_16x16x32_bf16 v[64:67], v[190:193], v[222:225], v[64:67]
	s_setprio 0
	s_barrier
; #define PG8_STAGE(bufoff, gbase, voff) do { _Pragma("unroll") for (int _i = 0; _i < 2; ++_i) \
;         __builtin_amdgcn_global_load_lds((const unsigned*)((const char*)(gbase) + (voff)[_i]), (PG8_LAS unsigned*)(lds + (bufoff) + ldsw + _i * 8192), 16, 0, 0); } while (0)
; #define PG8_LDA(dst, b, h) do { _Pragma("unroll") for (int m = 0; m < 4; ++m) _Pragma("unroll") for (int k = 0; k < 2; ++k) dst[m][k] = *(const PG8_LAS bf16x8*)(lds + PG8_SA(b, h) + aoff + m * 2048 + k * 1024); } while (0)
; #define PG8_MMA(ai, bj, At, Bt) do { __builtin_amdgcn_s_setprio(1); _Pragma("unroll") for (int m = 0; m < 4; ++m) _Pragma("unroll") for (int n = 0; n < 2; ++n) _Pragma("unroll") for (int k = 0; k < 2; ++k) \
;         acc[ai][bj][m][n] = __builtin_amdgcn_mfma_f32_16x16x32_bf16(Bt[n][k], At[m][k], acc[ai][bj][m][n], 0, 0, 0); __builtin_amdgcn_s_setprio(0); } while (0)
; #define PG8_WAIT_V(n) asm volatile("s_waitcnt vmcnt(" #n ")" ::: "memory")
; #define PG8_WAIT_L(n) asm volatile("s_waitcnt lgkmcnt(" #n ")" ::: "memory")
; #define PG8_BAR __builtin_amdgcn_s_barrier()
; #define PG8_SCHED __builtin_amdgcn_sched_barrier(0)
; template <class Epi, class Sched, bool ALIGN_EPI = false, bool SP2 = false>
; __device__ __forceinline__ void gemm_phase(PG8_LAS unsigned char* lds, const Gemm g, const Sched& S, const Epi& E) {
;     ...
;             PG8_LDA(At, 1, 1); PG8_STAGE(PG8_SB(1, 0), b3, voffB); PG8_STAGE(PG8_SB(1, 1), b3 + hstepB, voffB); PG8_STAGE(PG8_SA(1, 0), a3, voffA);
;             PG8_WAIT_V(8); PG8_WAIT_L(0); PG8_BAR; PG8_MMA(1, 0, At, B0); PG8_MMA(1, 1, At, B1); PG8_BAR; PG8_SCHED;
;     __device__ __forceinline__ void operator()(const f32x4 (&acc)[2][2][4][2], const pg8::Unit& u, int wr, int wc, int fr, int fq) const {
;         float* base = part + (size_t)(u.koff >> 10) * 8192 * 256;
; #pragma unroll
;         for (int ai = 0; ai < 2; ++ai)
; #pragma unroll
;             for (int m = 0; m < 4; ++m) {
;                 const int row = u.pm * 256 + ai * 128 + wr * 64 + m * 16 + fr;
; #pragma unroll
;                 for (int bj = 0; bj < 2; ++bj) {
;                     float* p = base + (size_t)row * 256 + 128 * bj + 32 * wc + 8 * fq;
;                     *(f32x4*)p = acc[ai][bj][m][0]; *(f32x4*)(p + 4) = acc[ai][bj][m][1];
;                 }
	s_add_i32 s16, s45, s15
	v_lshl_add_u64 v[182:183], v[182:183], 0, s[10:11]
	s_mov_b32 m0, s16
	ds_read_b128 v[194:197], v157 offset:49152
	ds_read_b128 v[198:201], v157 offset:50176
	ds_read_b128 v[202:205], v157 offset:51200
	ds_read_b128 v[206:209], v157 offset:52224
	ds_read_b128 v[210:213], v157 offset:53248
	ds_read_b128 v[214:217], v157 offset:54272
	ds_read_b128 v[218:221], v157 offset:55296
	ds_read_b128 v[222:225], v157 offset:56320
	global_load_lds_dwordx4 v[182:183], off
	s_add_i32 m0, s16, 0x2000
	s_add_u32 s12, s12, 0x80080
	v_lshl_add_u64 v[182:183], v[226:227], 0, s[10:11]
	s_addc_u32 s13, s13, 0
	s_add_i32 s16, s46, s15
	global_load_lds_dwordx4 v[182:183], off
	v_lshl_add_u64 v[182:183], s[12:13], 0, v[132:133]
	s_mov_b32 m0, s16
	s_nop 0
	global_load_lds_dwordx4 v[182:183], off
	v_lshl_add_u64 v[182:183], s[12:13], 0, v[128:129]
	s_add_i32 m0, s16, 0x2000
	s_nop 0
	global_load_lds_dwordx4 v[182:183], off
	v_lshl_add_u64 v[182:183], v[228:229], 0, s[10:11]
	s_mov_b32 m0, s30
	s_nop 0
	global_load_lds_dwordx4 v[182:183], off
	v_lshl_add_u64 v[182:183], v[230:231], 0, s[10:11]
	s_mov_b32 m0, s31
	s_nop 0
	global_load_lds_dwordx4 v[182:183], off
	s_waitcnt vmcnt(8) lgkmcnt(0)
	s_setprio 1
	s_barrier
	v_mfma_f32_16x16x32_bf16 v[60:63], v[158:161], v[194:197], v[60:63]
	v_mfma_f32_16x16x32_bf16 v[56:59], v[166:169], v[194:197], v[56:59]
	v_mfma_f32_16x16x32_bf16 v[52:55], v[158:161], v[202:205], v[52:55]
	v_mfma_f32_16x16x32_bf16 v[48:51], v[166:169], v[202:205], v[48:51]
	v_mfma_f32_16x16x32_bf16 v[44:47], v[158:161], v[210:213], v[44:47]
	v_mfma_f32_16x16x32_bf16 v[36:39], v[166:169], v[210:213], v[36:39]
	v_mfma_f32_16x16x32_bf16 v[28:31], v[158:161], v[218:221], v[28:31]
	v_mfma_f32_16x16x32_bf16 v[20:23], v[166:169], v[218:221], v[20:23]
	v_mfma_f32_16x16x32_bf16 v[60:63], v[162:165], v[198:201], v[60:63]
	v_mfma_f32_16x16x32_bf16 v[56:59], v[170:173], v[198:201], v[56:59]
	v_mfma_f32_16x16x32_bf16 v[52:55], v[162:165], v[206:209], v[52:55]
	v_mfma_f32_16x16x32_bf16 v[48:51], v[170:173], v[206:209], v[48:51]
	v_mfma_f32_16x16x32_bf16 v[44:47], v[162:165], v[214:217], v[44:47]
	v_mfma_f32_16x16x32_bf16 v[36:39], v[170:173], v[214:217], v[36:39]
	v_mfma_f32_16x16x32_bf16 v[28:31], v[162:165], v[222:225], v[28:31]
	v_mfma_f32_16x16x32_bf16 v[20:23], v[170:173], v[222:225], v[20:23]
	v_mfma_f32_16x16x32_bf16 v[40:43], v[174:177], v[194:197], v[40:43]
	v_mfma_f32_16x16x32_bf16 v[32:35], v[186:189], v[194:197], v[32:35]
	v_mfma_f32_16x16x32_bf16 v[24:27], v[174:177], v[202:205], v[24:27]
	v_mfma_f32_16x16x32_bf16 v[16:19], v[186:189], v[202:205], v[16:19]
	v_mfma_f32_16x16x32_bf16 v[12:15], v[174:177], v[210:213], v[12:15]
	v_mfma_f32_16x16x32_bf16 v[8:11], v[186:189], v[210:213], v[8:11]
	v_mfma_f32_16x16x32_bf16 v[4:7], v[174:177], v[218:221], v[4:7]
	v_mfma_f32_16x16x32_bf16 v[0:3], v[186:189], v[218:221], v[0:3]
	v_mfma_f32_16x16x32_bf16 v[40:43], v[178:181], v[198:201], v[40:43]
	v_mfma_f32_16x16x32_bf16 v[32:35], v[190:193], v[198:201], v[32:35]
	v_mfma_f32_16x16x32_bf16 v[24:27], v[178:181], v[206:209], v[24:27]
	v_mfma_f32_16x16x32_bf16 v[16:19], v[190:193], v[206:209], v[16:19]
	v_mfma_f32_16x16x32_bf16 v[12:15], v[178:181], v[214:217], v[12:15]
	v_mfma_f32_16x16x32_bf16 v[8:11], v[190:193], v[214:217], v[8:11]
	v_mfma_f32_16x16x32_bf16 v[4:7], v[178:181], v[222:225], v[4:7]
	v_mfma_f32_16x16x32_bf16 v[0:3], v[190:193], v[222:225], v[0:3]
	s_setprio 0
	s_barrier
	s_add_i32 s44, s44, 2
	s_add_u32 s0, s0, 0x100
	s_addc_u32 s1, s1, 0
	s_add_u32 s42, s42, 0x100
	s_addc_u32 s43, s43, 0
	s_cmp_gt_u32 s44, 5
	s_cbranch_scc0 .LBB0_470
	s_ashr_i32 s0, s24, 10
	s_ashr_i32 s1, s0, 31
	s_lshl_b64 s[0:1], s[0:1], 23
	v_lshl_add_u64 v[158:159], v[138:139], 0, s[0:1]
	s_lshl_b32 s0, s23, 8
	v_add_u32_e32 v136, s0, v148
	v_lshlrev_b64 v[160:161], 10, v[136:137]
	v_lshl_add_u64 v[160:161], v[158:159], 0, v[160:161]
	global_store_dwordx4 v[160:161], v[124:127], off
	global_store_dwordx4 v[160:161], v[120:123], off offset:16
	global_store_dwordx4 v[160:161], v[104:107], off offset:512
	global_store_dwordx4 v[160:161], v[96:99], off offset:528
	s_and_b64 vcc, exec, vcc
	s_mov_b32 s24, s35
	v_add_u32_e32 v96, s0, v152
	v_mov_b32_e32 v97, v137
	v_lshlrev_b64 v[96:97], 10, v[96:97]
	v_lshl_add_u64 v[96:97], v[158:159], 0, v[96:97]
	global_store_dwordx4 v[96:97], v[116:119], off
	global_store_dwordx4 v[96:97], v[112:115], off offset:16
	global_store_dwordx4 v[96:97], v[88:91], off offset:512
	global_store_dwordx4 v[96:97], v[80:83], off offset:528
	s_mov_b32 s23, s37
	s_nop 0
	v_add_u32_e32 v80, s0, v153
	v_mov_b32_e32 v81, v137
	v_lshlrev_b64 v[80:81], 10, v[80:81]
	v_lshl_add_u64 v[80:81], v[158:159], 0, v[80:81]
	global_store_dwordx4 v[80:81], v[108:111], off
	global_store_dwordx4 v[80:81], v[100:103], off offset:16
	global_store_dwordx4 v[80:81], v[76:79], off offset:512
	global_store_dwordx4 v[80:81], v[72:75], off offset:528
	s_nop 1
	v_add_u32_e32 v72, s0, v154
	v_mov_b32_e32 v73, v137
	v_lshlrev_b64 v[72:73], 10, v[72:73]
	v_lshl_add_u64 v[72:73], v[158:159], 0, v[72:73]
	global_store_dwordx4 v[72:73], v[92:95], off
	global_store_dwordx4 v[72:73], v[84:87], off offset:16
	global_store_dwordx4 v[72:73], v[68:71], off offset:512
	global_store_dwordx4 v[72:73], v[64:67], off offset:528
	s_nop 1
	v_add_u32_e32 v64, 0x80, v136
	v_mov_b32_e32 v65, v137
	v_lshlrev_b64 v[64:65], 10, v[64:65]
	v_lshl_add_u64 v[64:65], v[158:159], 0, v[64:65]
	global_store_dwordx4 v[64:65], v[60:63], off
	global_store_dwordx4 v[64:65], v[56:59], off offset:16
	global_store_dwordx4 v[64:65], v[40:43], off offset:512
	global_store_dwordx4 v[64:65], v[32:35], off offset:528
	s_nop 1
	v_add_u32_e32 v32, 0x90, v136
	v_mov_b32_e32 v33, v137
	v_lshlrev_b64 v[32:33], 10, v[32:33]
	v_lshl_add_u64 v[32:33], v[158:159], 0, v[32:33]
	global_store_dwordx4 v[32:33], v[52:55], off
	global_store_dwordx4 v[32:33], v[48:51], off offset:16
	global_store_dwordx4 v[32:33], v[24:27], off offset:512
	global_store_dwordx4 v[32:33], v[16:19], off offset:528
	s_nop 1
	v_add_u32_e32 v16, 0xa0, v136
	v_mov_b32_e32 v17, v137
	v_lshlrev_b64 v[16:17], 10, v[16:17]
	v_lshl_add_u64 v[16:17], v[158:159], 0, v[16:17]
	v_add_u32_e32 v136, 0xb0, v136
	global_store_dwordx4 v[16:17], v[44:47], off
	global_store_dwordx4 v[16:17], v[36:39], off offset:16
	global_store_dwordx4 v[16:17], v[12:15], off offset:512
	global_store_dwordx4 v[16:17], v[8:11], off offset:528
	s_nop 1
	v_lshlrev_b64 v[8:9], 10, v[136:137]
	v_lshl_add_u64 v[8:9], v[158:159], 0, v[8:9]
	global_store_dwordx4 v[8:9], v[28:31], off
	global_store_dwordx4 v[8:9], v[20:23], off offset:16
	global_store_dwordx4 v[8:9], v[4:7], off offset:512
	global_store_dwordx4 v[8:9], v[0:3], off offset:528
	s_cbranch_vccz .LBB0_469
	s_waitcnt vmcnt(0)
	s_cmpk_gt_u32 s14, 0xff
	s_cbranch_scc1 .LBB0_474
	s_barrier

; #define PG8_STAGE(bufoff, gbase, voff) do { _Pragma("unroll") for (int _i = 0; _i < 2; ++_i) \
;         __builtin_amdgcn_global_load_lds((const unsigned*)((const char*)(gbase) + (voff)[_i]), (PG8_LAS unsigned*)(lds + (bufoff) + ldsw + _i * 8192), 16, 0, 0); } while (0)
; #define PG8_LDA(dst, b, h) do { _Pragma("unroll") for (int m = 0; m < 4; ++m) _Pragma("unroll") for (int k = 0; k < 2; ++k) dst[m][k] = *(const PG8_LAS bf16x8*)(lds + PG8_SA(b, h) + aoff + m * 2048 + k * 1024); } while (0)
; #define PG8_LDB(dst, b, h) do { _Pragma("unroll") for (int n = 0; n < 2; ++n) _Pragma("unroll") for (int k = 0; k < 2; ++k) dst[n][k] = *(const PG8_LAS bf16x8*)(lds + PG8_SB(b, h) + boff + n * 2048 + k * 1024); } while (0)
; #define PG8_MMA(ai, bj, At, Bt) do { __builtin_amdgcn_s_setprio(1); _Pragma("unroll") for (int m = 0; m < 4; ++m) _Pragma("unroll") for (int n = 0; n < 2; ++n) _Pragma("unroll") for (int k = 0; k < 2; ++k) \
;         acc[ai][bj][m][n] = __builtin_amdgcn_mfma_f32_16x16x32_bf16(Bt[n][k], At[m][k], acc[ai][bj][m][n], 0, 0, 0); __builtin_amdgcn_s_setprio(0); } while (0)
; #define PG8_WAIT_V(n) asm volatile("s_waitcnt vmcnt(" #n ")" ::: "memory")
; #define PG8_WAIT_L(n) asm volatile("s_waitcnt lgkmcnt(" #n ")" ::: "memory")
; #define PG8_BAR __builtin_amdgcn_s_barrier()
; #define PG8_SCHED __builtin_amdgcn_sched_barrier(0)
; template <class Epi, class Sched, bool ALIGN_EPI = false, bool SP2 = false>
; __device__ __forceinline__ void gemm_phase(PG8_LAS unsigned char* lds, const Gemm g, const Sched& S, const Epi& E) {
;     ...
;             PG8_LDB(B0, 0, 0); PG8_LDB(B1, 0, 1); PG8_SCHED; PG8_LDA(At, 0, 0); PG8_STAGE(PG8_SA(1, 1), a1 + hstepA, voffA);
;             PG8_WAIT_V(8); PG8_WAIT_L(0); PG8_BAR; PG8_MMA(0, 0, At, B0); PG8_MMA(0, 1, At, B1); PG8_BAR; PG8_SCHED;
;             PG8_LDA(At, 0, 1); PG8_STAGE(PG8_SB(0, 0), b2, voffB); PG8_STAGE(PG8_SB(0, 1), b2 + hstepB, voffB); PG8_STAGE(PG8_SA(0, 0), a2, voffA);
;             PG8_WAIT_V(8); PG8_WAIT_L(0); PG8_BAR; PG8_MMA(1, 0, At, B0); PG8_MMA(1, 1, At, B1); PG8_BAR; PG8_SCHED;
.LBB0_935:
	ds_read_b128 v[120:123], v237
	ds_read_b128 v[124:127], v237 offset:1024
	ds_read_b128 v[136:139], v237 offset:2048
	ds_read_b128 v[140:143], v237 offset:3072
	ds_read_b128 v[144:147], v238
	ds_read_b128 v[148:151], v238 offset:1024
	ds_read_b128 v[152:155], v238 offset:2048
	ds_read_b128 v[156:159], v238 offset:3072
	s_add_u32 s38, s36, 0xfffc0080
	s_addc_u32 s39, s37, -1
	s_cmp_eq_u32 s58, 12
	s_cselect_b32 s41, s9, s39
	s_cselect_b32 s40, s27, s38
	s_cselect_b32 s39, s25, s57
	s_cselect_b32 s38, s35, s56
	v_lshl_add_u64 v[214:215], s[36:37], 0, v[198:199]
	s_add_i32 m0, s44, 0xc000
	ds_read_b128 v[160:163], v239
	ds_read_b128 v[164:167], v239 offset:1024
	ds_read_b128 v[168:171], v239 offset:2048
	ds_read_b128 v[172:175], v239 offset:3072
	ds_read_b128 v[176:179], v239 offset:4096
	ds_read_b128 v[180:183], v239 offset:5120
	ds_read_b128 v[206:209], v239 offset:6144
	ds_read_b128 v[210:213], v239 offset:7168
	global_load_lds_dwordx4 v[214:215], off
	v_lshl_add_u64 v[214:215], s[36:37], 0, v[200:201]
	s_add_i32 m0, s44, 0xe000
	s_nop 0
	global_load_lds_dwordx4 v[214:215], off
	s_waitcnt vmcnt(8) lgkmcnt(0)
	s_setprio 1
	s_barrier
	v_mfma_f32_16x16x32_bf16 v[132:135], v[120:123], v[160:163], v[132:135]
	v_mfma_f32_16x16x32_bf16 v[128:131], v[136:139], v[160:163], v[128:131]
	v_mfma_f32_16x16x32_bf16 v[108:111], v[120:123], v[168:171], v[108:111]
	v_mfma_f32_16x16x32_bf16 v[104:107], v[136:139], v[168:171], v[104:107]
	v_mfma_f32_16x16x32_bf16 v[92:95], v[120:123], v[176:179], v[92:95]
	v_mfma_f32_16x16x32_bf16 v[88:91], v[136:139], v[176:179], v[88:91]
	v_mfma_f32_16x16x32_bf16 v[76:79], v[120:123], v[206:209], v[76:79]
	v_mfma_f32_16x16x32_bf16 v[72:75], v[136:139], v[206:209], v[72:75]
	v_mfma_f32_16x16x32_bf16 v[132:135], v[124:127], v[164:167], v[132:135]
	v_mfma_f32_16x16x32_bf16 v[128:131], v[140:143], v[164:167], v[128:131]
	v_mfma_f32_16x16x32_bf16 v[108:111], v[124:127], v[172:175], v[108:111]
	v_mfma_f32_16x16x32_bf16 v[104:107], v[140:143], v[172:175], v[104:107]
	v_mfma_f32_16x16x32_bf16 v[92:95], v[124:127], v[180:183], v[92:95]
	v_mfma_f32_16x16x32_bf16 v[88:91], v[140:143], v[180:183], v[88:91]
	v_mfma_f32_16x16x32_bf16 v[76:79], v[124:127], v[210:213], v[76:79]
	v_mfma_f32_16x16x32_bf16 v[72:75], v[140:143], v[210:213], v[72:75]
	v_mfma_f32_16x16x32_bf16 v[116:119], v[144:147], v[160:163], v[116:119]
	v_mfma_f32_16x16x32_bf16 v[112:115], v[152:155], v[160:163], v[112:115]
	v_mfma_f32_16x16x32_bf16 v[100:103], v[144:147], v[168:171], v[100:103]
	v_mfma_f32_16x16x32_bf16 v[96:99], v[152:155], v[168:171], v[96:99]
	v_mfma_f32_16x16x32_bf16 v[84:87], v[144:147], v[176:179], v[84:87]
	v_mfma_f32_16x16x32_bf16 v[80:83], v[152:155], v[176:179], v[80:83]
	v_mfma_f32_16x16x32_bf16 v[68:71], v[144:147], v[206:209], v[68:71]
	v_mfma_f32_16x16x32_bf16 v[64:67], v[152:155], v[206:209], v[64:67]
	v_mfma_f32_16x16x32_bf16 v[116:119], v[148:151], v[164:167], v[116:119]
	v_mfma_f32_16x16x32_bf16 v[112:115], v[156:159], v[164:167], v[112:115]
	v_mfma_f32_16x16x32_bf16 v[100:103], v[148:151], v[172:175], v[100:103]
	v_mfma_f32_16x16x32_bf16 v[96:99], v[156:159], v[172:175], v[96:99]
	v_mfma_f32_16x16x32_bf16 v[84:87], v[148:151], v[180:183], v[84:87]
	v_mfma_f32_16x16x32_bf16 v[80:83], v[156:159], v[180:183], v[80:83]
	v_mfma_f32_16x16x32_bf16 v[68:71], v[148:151], v[210:213], v[68:71]
	v_mfma_f32_16x16x32_bf16 v[64:67], v[156:159], v[210:213], v[64:67]
	s_setprio 0
	s_barrier
	s_add_i32 s59, s53, s43
	v_lshl_add_u64 v[214:215], s[38:39], 0, v[188:189]
	s_mov_b32 m0, s59
	ds_read_b128 v[160:163], v239 offset:16384
	ds_read_b128 v[164:167], v239 offset:17408
	ds_read_b128 v[168:171], v239 offset:18432
	ds_read_b128 v[172:175], v239 offset:19456
	ds_read_b128 v[176:179], v239 offset:20480
	ds_read_b128 v[180:183], v239 offset:21504
	ds_read_b128 v[206:209], v239 offset:22528
	ds_read_b128 v[210:213], v239 offset:23552
	global_load_lds_dwordx4 v[214:215], off
	s_add_i32 m0, s59, 0x2000
	s_add_u32 s60, s38, 0x40000
	v_lshl_add_u64 v[216:217], s[38:39], 0, v[192:193]
	s_addc_u32 s61, s39, 0
	s_add_i32 s59, s54, s43
	global_load_lds_dwordx4 v[216:217], off
	v_lshl_add_u64 v[218:219], s[60:61], 0, v[188:189]
	s_mov_b32 m0, s59
	v_lshl_add_u64 v[220:221], s[40:41], 0, v[190:191]
	global_load_lds_dwordx4 v[218:219], off
	v_lshl_add_u64 v[218:219], s[60:61], 0, v[192:193]
	s_add_i32 m0, s59, 0x2000
	s_nop 0
	global_load_lds_dwordx4 v[218:219], off
	v_lshl_add_u64 v[218:219], s[40:41], 0, v[186:187]
	s_mov_b32 m0, s44
	s_nop 0
	global_load_lds_dwordx4 v[218:219], off
	s_mov_b32 m0, s45
	s_nop 0
	global_load_lds_dwordx4 v[220:221], off
	s_waitcnt vmcnt(8) lgkmcnt(0)
	s_setprio 1
	s_barrier
; #define PG8_STAGE(bufoff, gbase, voff) do { _Pragma("unroll") for (int _i = 0; _i < 2; ++_i) \
;         __builtin_amdgcn_global_load_lds((const unsigned*)((const char*)(gbase) + (voff)[_i]), (PG8_LAS unsigned*)(lds + (bufoff) + ldsw + _i * 8192), 16, 0, 0); } while (0)
; #define PG8_LDA(dst, b, h) do { _Pragma("unroll") for (int m = 0; m < 4; ++m) _Pragma("unroll") for (int k = 0; k < 2; ++k) dst[m][k] = *(const PG8_LAS bf16x8*)(lds + PG8_SA(b, h) + aoff + m * 2048 + k * 1024); } while (0)
; #define PG8_LDB(dst, b, h) do { _Pragma("unroll") for (int n = 0; n < 2; ++n) _Pragma("unroll") for (int k = 0; k < 2; ++k) dst[n][k] = *(const PG8_LAS bf16x8*)(lds + PG8_SB(b, h) + boff + n * 2048 + k * 1024); } while (0)
; #define PG8_MMA(ai, bj, At, Bt) do { __builtin_amdgcn_s_setprio(1); _Pragma("unroll") for (int m = 0; m < 4; ++m) _Pragma("unroll") for (int n = 0; n < 2; ++n) _Pragma("unroll") for (int k = 0; k < 2; ++k) \
;         acc[ai][bj][m][n] = __builtin_amdgcn_mfma_f32_16x16x32_bf16(Bt[n][k], At[m][k], acc[ai][bj][m][n], 0, 0, 0); __builtin_amdgcn_s_setprio(0); } while (0)
; #define PG8_WAIT_V(n) asm volatile("s_waitcnt vmcnt(" #n ")" ::: "memory")
; template <class Epi, class Sched, bool ALIGN_EPI = false, bool SP2 = false>
; __device__ __forceinline__ void gemm_phase(PG8_LAS unsigned char* lds, const Gemm g, const Sched& S, const Epi& E) {
;     ...
;             PG8_LDB(B0, 0, 0); PG8_LDB(B1, 0, 1); PG8_SCHED; PG8_LDA(At, 0, 0); PG8_STAGE(PG8_SA(1, 1), a1 + hstepA, voffA);
;             PG8_WAIT_V(8); PG8_WAIT_L(0); PG8_BAR; PG8_MMA(0, 0, At, B0); PG8_MMA(0, 1, At, B1); PG8_BAR; PG8_SCHED;
;             PG8_LDA(At, 0, 1); PG8_STAGE(PG8_SB(0, 0), b2, voffB); PG8_STAGE(PG8_SB(0, 1), b2 + hstepB, voffB); PG8_STAGE(PG8_SA(0, 0), a2, voffA);
;             PG8_WAIT_V(8); PG8_WAIT_L(0); PG8_BAR; PG8_MMA(1, 0, At, B0); PG8_MMA(1, 1, At, B1); PG8_BAR; PG8_SCHED;
;             PG8_LDB(B0, 1, 0); PG8_LDB(B1, 1, 1); PG8_SCHED; PG8_LDA(At, 1, 0); PG8_STAGE(PG8_SA(0, 1), a2 + hstepA, voffA);
;             PG8_WAIT_V(8); PG8_WAIT_L(0); PG8_BAR; PG8_MMA(0, 0, At, B0); PG8_MMA(0, 1, At, B1); PG8_BAR; PG8_SCHED;
;             PG8_LDA(At, 1, 1); PG8_STAGE(PG8_SB(1, 0), b3, voffB); PG8_STAGE(PG8_SB(1, 1), b3 + hstepB, voffB); PG8_STAGE(PG8_SA(1, 0), a3, voffA);
;             PG8_WAIT_V(8); PG8_WAIT_L(0); PG8_BAR; PG8_MMA(1, 0, At, B0); PG8_MMA(1, 1, At, B1); PG8_BAR; PG8_SCHED;
	v_mfma_f32_16x16x32_bf16 v[60:63], v[120:123], v[160:163], v[60:63]
	v_mfma_f32_16x16x32_bf16 v[56:59], v[136:139], v[160:163], v[56:59]
	v_mfma_f32_16x16x32_bf16 v[44:47], v[120:123], v[168:171], v[44:47]
	v_mfma_f32_16x16x32_bf16 v[40:43], v[136:139], v[168:171], v[40:43]
	v_mfma_f32_16x16x32_bf16 v[28:31], v[120:123], v[176:179], v[28:31]
	v_mfma_f32_16x16x32_bf16 v[24:27], v[136:139], v[176:179], v[24:27]
	v_mfma_f32_16x16x32_bf16 v[12:15], v[120:123], v[206:209], v[12:15]
	v_mfma_f32_16x16x32_bf16 v[8:11], v[136:139], v[206:209], v[8:11]
	v_mfma_f32_16x16x32_bf16 v[60:63], v[124:127], v[164:167], v[60:63]
	v_mfma_f32_16x16x32_bf16 v[56:59], v[140:143], v[164:167], v[56:59]
	v_mfma_f32_16x16x32_bf16 v[44:47], v[124:127], v[172:175], v[44:47]
	v_mfma_f32_16x16x32_bf16 v[40:43], v[140:143], v[172:175], v[40:43]
	v_mfma_f32_16x16x32_bf16 v[28:31], v[124:127], v[180:183], v[28:31]
	v_mfma_f32_16x16x32_bf16 v[24:27], v[140:143], v[180:183], v[24:27]
	v_mfma_f32_16x16x32_bf16 v[12:15], v[124:127], v[210:213], v[12:15]
	v_mfma_f32_16x16x32_bf16 v[8:11], v[140:143], v[210:213], v[8:11]
	v_mfma_f32_16x16x32_bf16 v[52:55], v[144:147], v[160:163], v[52:55]
	v_mfma_f32_16x16x32_bf16 v[48:51], v[152:155], v[160:163], v[48:51]
	v_mfma_f32_16x16x32_bf16 v[36:39], v[144:147], v[168:171], v[36:39]
	v_mfma_f32_16x16x32_bf16 v[32:35], v[152:155], v[168:171], v[32:35]
	v_mfma_f32_16x16x32_bf16 v[20:23], v[144:147], v[176:179], v[20:23]
	v_mfma_f32_16x16x32_bf16 v[16:19], v[152:155], v[176:179], v[16:19]
	v_mfma_f32_16x16x32_bf16 v[4:7], v[144:147], v[206:209], v[4:7]
	v_mfma_f32_16x16x32_bf16 v[0:3], v[152:155], v[206:209], v[0:3]
	v_mfma_f32_16x16x32_bf16 v[52:55], v[148:151], v[164:167], v[52:55]
	v_mfma_f32_16x16x32_bf16 v[48:51], v[156:159], v[164:167], v[48:51]
	v_mfma_f32_16x16x32_bf16 v[36:39], v[148:151], v[172:175], v[36:39]
	v_mfma_f32_16x16x32_bf16 v[32:35], v[156:159], v[172:175], v[32:35]
	v_mfma_f32_16x16x32_bf16 v[20:23], v[148:151], v[180:183], v[20:23]
	v_mfma_f32_16x16x32_bf16 v[16:19], v[156:159], v[180:183], v[16:19]
	v_mfma_f32_16x16x32_bf16 v[4:7], v[148:151], v[210:213], v[4:7]
	v_mfma_f32_16x16x32_bf16 v[0:3], v[156:159], v[210:213], v[0:3]
	s_setprio 0
	s_barrier
	s_add_i32 s59, 0, 0x18000
	s_add_i32 s60, 0, 0x1c000
	v_add_u32_e32 v140, s59, v234
	v_add_u32_e32 v156, s60, v234
	ds_read_b128 v[120:123], v140
	ds_read_b128 v[124:127], v140 offset:1024
	ds_read_b128 v[136:139], v140 offset:2048
	ds_read_b128 v[140:143], v140 offset:3072
	ds_read_b128 v[144:147], v156
	ds_read_b128 v[148:151], v156 offset:1024
	ds_read_b128 v[152:155], v156 offset:2048
	ds_read_b128 v[156:159], v156 offset:3072
	s_add_u32 s40, s40, 0x40000
	s_addc_u32 s41, s41, 0
	s_mov_b32 m0, s46
	v_lshl_add_u64 v[222:223], s[40:41], 0, v[186:187]
	ds_read_b128 v[160:163], v239 offset:32768
	ds_read_b128 v[164:167], v239 offset:33792
	ds_read_b128 v[168:171], v239 offset:34816
	ds_read_b128 v[172:175], v239 offset:35840
	ds_read_b128 v[176:179], v239 offset:36864
	ds_read_b128 v[180:183], v239 offset:37888
	ds_read_b128 v[206:209], v239 offset:38912
	ds_read_b128 v[210:213], v239 offset:39936
	global_load_lds_dwordx4 v[222:223], off
	v_lshl_add_u64 v[222:223], s[40:41], 0, v[190:191]
	s_mov_b32 m0, s47
	s_nop 0
	global_load_lds_dwordx4 v[222:223], off
	s_waitcnt vmcnt(8) lgkmcnt(0)
	s_setprio 1
	s_barrier
	v_mfma_f32_16x16x32_bf16 v[132:135], v[120:123], v[160:163], v[132:135]
	v_mfma_f32_16x16x32_bf16 v[128:131], v[136:139], v[160:163], v[128:131]
	v_mfma_f32_16x16x32_bf16 v[108:111], v[120:123], v[168:171], v[108:111]
	v_mfma_f32_16x16x32_bf16 v[104:107], v[136:139], v[168:171], v[104:107]
	v_mfma_f32_16x16x32_bf16 v[92:95], v[120:123], v[176:179], v[92:95]
	v_mfma_f32_16x16x32_bf16 v[88:91], v[136:139], v[176:179], v[88:91]
	v_mfma_f32_16x16x32_bf16 v[76:79], v[120:123], v[206:209], v[76:79]
	v_mfma_f32_16x16x32_bf16 v[72:75], v[136:139], v[206:209], v[72:75]
	v_mfma_f32_16x16x32_bf16 v[132:135], v[124:127], v[164:167], v[132:135]
	v_mfma_f32_16x16x32_bf16 v[128:131], v[140:143], v[164:167], v[128:131]
	v_mfma_f32_16x16x32_bf16 v[108:111], v[124:127], v[172:175], v[108:111]
	v_mfma_f32_16x16x32_bf16 v[104:107], v[140:143], v[172:175], v[104:107]
	v_mfma_f32_16x16x32_bf16 v[92:95], v[124:127], v[180:183], v[92:95]
	v_mfma_f32_16x16x32_bf16 v[88:91], v[140:143], v[180:183], v[88:91]
	v_mfma_f32_16x16x32_bf16 v[76:79], v[124:127], v[210:213], v[76:79]
	v_mfma_f32_16x16x32_bf16 v[72:75], v[140:143], v[210:213], v[72:75]
	v_mfma_f32_16x16x32_bf16 v[116:119], v[144:147], v[160:163], v[116:119]
	v_mfma_f32_16x16x32_bf16 v[112:115], v[152:155], v[160:163], v[112:115]
	v_mfma_f32_16x16x32_bf16 v[100:103], v[144:147], v[168:171], v[100:103]
	v_mfma_f32_16x16x32_bf16 v[96:99], v[152:155], v[168:171], v[96:99]
	v_mfma_f32_16x16x32_bf16 v[84:87], v[144:147], v[176:179], v[84:87]
	v_mfma_f32_16x16x32_bf16 v[80:83], v[152:155], v[176:179], v[80:83]
	v_mfma_f32_16x16x32_bf16 v[68:71], v[144:147], v[206:209], v[68:71]
	v_mfma_f32_16x16x32_bf16 v[64:67], v[152:155], v[206:209], v[64:67]
	v_mfma_f32_16x16x32_bf16 v[116:119], v[148:151], v[164:167], v[116:119]
	v_mfma_f32_16x16x32_bf16 v[112:115], v[156:159], v[164:167], v[112:115]
	v_mfma_f32_16x16x32_bf16 v[100:103], v[148:151], v[172:175], v[100:103]
	v_mfma_f32_16x16x32_bf16 v[96:99], v[156:159], v[172:175], v[96:99]
	v_mfma_f32_16x16x32_bf16 v[84:87], v[148:151], v[180:183], v[84:87]
	v_mfma_f32_16x16x32_bf16 v[80:83], v[156:159], v[180:183], v[80:83]
	v_mfma_f32_16x16x32_bf16 v[68:71], v[148:151], v[210:213], v[68:71]
	v_mfma_f32_16x16x32_bf16 v[64:67], v[156:159], v[210:213], v[64:67]
	s_setprio 0
	s_barrier
; #define PG8_STAGE(bufoff, gbase, voff) do { _Pragma("unroll") for (int _i = 0; _i < 2; ++_i) \
;         __builtin_amdgcn_global_load_lds((const unsigned*)((const char*)(gbase) + (voff)[_i]), (PG8_LAS unsigned*)(lds + (bufoff) + ldsw + _i * 8192), 16, 0, 0); } while (0)
; #define PG8_LDA(dst, b, h) do { _Pragma("unroll") for (int m = 0; m < 4; ++m) _Pragma("unroll") for (int k = 0; k < 2; ++k) dst[m][k] = *(const PG8_LAS bf16x8*)(lds + PG8_SA(b, h) + aoff + m * 2048 + k * 1024); } while (0)
; #define PG8_MMA(ai, bj, At, Bt) do { __builtin_amdgcn_s_setprio(1); _Pragma("unroll") for (int m = 0; m < 4; ++m) _Pragma("unroll") for (int n = 0; n < 2; ++n) _Pragma("unroll") for (int k = 0; k < 2; ++k) \
;         acc[ai][bj][m][n] = __builtin_amdgcn_mfma_f32_16x16x32_bf16(Bt[n][k], At[m][k], acc[ai][bj][m][n], 0, 0, 0); __builtin_amdgcn_s_setprio(0); } while (0)
; #define PG8_WAIT_V(n) asm volatile("s_waitcnt vmcnt(" #n ")" ::: "memory")
; #define PG8_WAIT_L(n) asm volatile("s_waitcnt lgkmcnt(" #n ")" ::: "memory")
; #define PG8_BAR __builtin_amdgcn_s_barrier()
; #define PG8_SCHED __builtin_amdgcn_sched_barrier(0)
; template <class Epi, class Sched, bool ALIGN_EPI = false, bool SP2 = false>
; __device__ __forceinline__ void gemm_phase(PG8_LAS unsigned char* lds, const Gemm g, const Sched& S, const Epi& E) {
;     ...
;             PG8_LDA(At, 1, 1); PG8_STAGE(PG8_SB(1, 0), b3, voffB); PG8_STAGE(PG8_SB(1, 1), b3 + hstepB, voffB); PG8_STAGE(PG8_SA(1, 0), a3, voffA);
;             PG8_WAIT_V(8); PG8_WAIT_L(0); PG8_BAR; PG8_MMA(1, 0, At, B0); PG8_MMA(1, 1, At, B1); PG8_BAR; PG8_SCHED;
;     ...
;         if constexpr (ALIGN_EPI) { if (wr == 0) PG8_BAR; }
	s_add_i32 s40, s59, s43
	v_lshl_add_u64 v[214:215], v[214:215], 0, s[20:21]
	s_mov_b32 m0, s40
	ds_read_b128 v[160:163], v239 offset:49152
	ds_read_b128 v[164:167], v239 offset:50176
	ds_read_b128 v[168:171], v239 offset:51200
	ds_read_b128 v[172:175], v239 offset:52224
	ds_read_b128 v[176:179], v239 offset:53248
	ds_read_b128 v[180:183], v239 offset:54272
	ds_read_b128 v[206:209], v239 offset:55296
	ds_read_b128 v[210:213], v239 offset:56320
	global_load_lds_dwordx4 v[214:215], off
	s_add_i32 m0, s40, 0x2000
	s_add_u32 s38, s38, 0x40080
	v_lshl_add_u64 v[214:215], v[216:217], 0, s[20:21]
	s_addc_u32 s39, s39, 0
	s_add_i32 s40, s60, s43
	global_load_lds_dwordx4 v[214:215], off
	v_lshl_add_u64 v[214:215], s[38:39], 0, v[188:189]
	s_mov_b32 m0, s40
	s_nop 0
	global_load_lds_dwordx4 v[214:215], off
	v_lshl_add_u64 v[214:215], s[38:39], 0, v[192:193]
	s_add_i32 m0, s40, 0x2000
	s_nop 0
	global_load_lds_dwordx4 v[214:215], off
	v_lshl_add_u64 v[214:215], v[218:219], 0, s[20:21]
	s_mov_b32 m0, s48
	s_nop 0
	global_load_lds_dwordx4 v[214:215], off
	v_lshl_add_u64 v[214:215], v[220:221], 0, s[20:21]
	s_mov_b32 m0, s49
	s_nop 0
	global_load_lds_dwordx4 v[214:215], off
	s_waitcnt vmcnt(8) lgkmcnt(0)
	s_setprio 1
	s_barrier
	v_mfma_f32_16x16x32_bf16 v[60:63], v[120:123], v[160:163], v[60:63]
	v_mfma_f32_16x16x32_bf16 v[56:59], v[136:139], v[160:163], v[56:59]
	v_mfma_f32_16x16x32_bf16 v[44:47], v[120:123], v[168:171], v[44:47]
	v_mfma_f32_16x16x32_bf16 v[40:43], v[136:139], v[168:171], v[40:43]
	v_mfma_f32_16x16x32_bf16 v[28:31], v[120:123], v[176:179], v[28:31]
	v_mfma_f32_16x16x32_bf16 v[24:27], v[136:139], v[176:179], v[24:27]
	v_mfma_f32_16x16x32_bf16 v[12:15], v[120:123], v[206:209], v[12:15]
	v_mfma_f32_16x16x32_bf16 v[8:11], v[136:139], v[206:209], v[8:11]
	v_mfma_f32_16x16x32_bf16 v[60:63], v[124:127], v[164:167], v[60:63]
	v_mfma_f32_16x16x32_bf16 v[56:59], v[140:143], v[164:167], v[56:59]
	v_mfma_f32_16x16x32_bf16 v[44:47], v[124:127], v[172:175], v[44:47]
	v_mfma_f32_16x16x32_bf16 v[40:43], v[140:143], v[172:175], v[40:43]
	v_mfma_f32_16x16x32_bf16 v[28:31], v[124:127], v[180:183], v[28:31]
	v_mfma_f32_16x16x32_bf16 v[24:27], v[140:143], v[180:183], v[24:27]
	v_mfma_f32_16x16x32_bf16 v[12:15], v[124:127], v[210:213], v[12:15]
	v_mfma_f32_16x16x32_bf16 v[8:11], v[140:143], v[210:213], v[8:11]
	v_mfma_f32_16x16x32_bf16 v[52:55], v[144:147], v[160:163], v[52:55]
	v_mfma_f32_16x16x32_bf16 v[48:51], v[152:155], v[160:163], v[48:51]
	v_mfma_f32_16x16x32_bf16 v[36:39], v[144:147], v[168:171], v[36:39]
	v_mfma_f32_16x16x32_bf16 v[32:35], v[152:155], v[168:171], v[32:35]
	v_mfma_f32_16x16x32_bf16 v[20:23], v[144:147], v[176:179], v[20:23]
	v_mfma_f32_16x16x32_bf16 v[16:19], v[152:155], v[176:179], v[16:19]
	v_mfma_f32_16x16x32_bf16 v[4:7], v[144:147], v[206:209], v[4:7]
	v_mfma_f32_16x16x32_bf16 v[0:3], v[152:155], v[206:209], v[0:3]
	v_mfma_f32_16x16x32_bf16 v[52:55], v[148:151], v[164:167], v[52:55]
	v_mfma_f32_16x16x32_bf16 v[48:51], v[156:159], v[164:167], v[48:51]
	v_mfma_f32_16x16x32_bf16 v[36:39], v[148:151], v[172:175], v[36:39]
	v_mfma_f32_16x16x32_bf16 v[32:35], v[156:159], v[172:175], v[32:35]
	v_mfma_f32_16x16x32_bf16 v[20:23], v[148:151], v[180:183], v[20:23]
	v_mfma_f32_16x16x32_bf16 v[16:19], v[156:159], v[180:183], v[16:19]
	v_mfma_f32_16x16x32_bf16 v[4:7], v[148:151], v[210:213], v[4:7]
	v_mfma_f32_16x16x32_bf16 v[0:3], v[156:159], v[210:213], v[0:3]
	s_setprio 0
	s_barrier
	s_add_i32 s58, s58, 2
	s_add_u32 s36, s36, 0x100
	s_addc_u32 s37, s37, 0
	s_add_u32 s56, s56, 0x100
	s_addc_u32 s57, s57, 0
	s_cmp_gt_u32 s58, 13
	s_cbranch_scc0 .LBB0_935
	s_and_b64 vcc, exec, s[22:23]
	s_cbranch_vccz .LBB0_938
	s_barrier

; #define PG8_STAGE(bufoff, gbase, voff) do { _Pragma("unroll") for (int _i = 0; _i < 2; ++_i) \
;         __builtin_amdgcn_global_load_lds((const unsigned*)((const char*)(gbase) + (voff)[_i]), (PG8_LAS unsigned*)(lds + (bufoff) + ldsw + _i * 8192), 16, 0, 0); } while (0)
; #define PG8_LDA(dst, b, h) do { _Pragma("unroll") for (int m = 0; m < 4; ++m) _Pragma("unroll") for (int k = 0; k < 2; ++k) dst[m][k] = *(const PG8_LAS bf16x8*)(lds + PG8_SA(b, h) + aoff + m * 2048 + k * 1024); } while (0)
; #define PG8_LDB(dst, b, h) do { _Pragma("unroll") for (int n = 0; n < 2; ++n) _Pragma("unroll") for (int k = 0; k < 2; ++k) dst[n][k] = *(const PG8_LAS bf16x8*)(lds + PG8_SB(b, h) + boff + n * 2048 + k * 1024); } while (0)
; #define PG8_MMA(ai, bj, At, Bt) do { __builtin_amdgcn_s_setprio(1); _Pragma("unroll") for (int m = 0; m < 4; ++m) _Pragma("unroll") for (int n = 0; n < 2; ++n) _Pragma("unroll") for (int k = 0; k < 2; ++k) \
;         acc[ai][bj][m][n] = __builtin_amdgcn_mfma_f32_16x16x32_bf16(Bt[n][k], At[m][k], acc[ai][bj][m][n], 0, 0, 0); __builtin_amdgcn_s_setprio(0); } while (0)
; #define PG8_WAIT_V(n) asm volatile("s_waitcnt vmcnt(" #n ")" ::: "memory")
; #define PG8_WAIT_L(n) asm volatile("s_waitcnt lgkmcnt(" #n ")" ::: "memory")
; #define PG8_BAR __builtin_amdgcn_s_barrier()
; #define PG8_SCHED __builtin_amdgcn_sched_barrier(0)
; template <class Epi, class Sched, bool ALIGN_EPI = false, bool SP2 = false>
; __device__ __forceinline__ void gemm_phase(PG8_LAS unsigned char* lds, const Gemm g, const Sched& S, const Epi& E) {
;     ...
;             PG8_LDB(B0, 0, 0); PG8_LDB(B1, 0, 1); PG8_SCHED; PG8_LDA(At, 0, 0); PG8_STAGE(PG8_SA(1, 1), a1 + hstepA, voffA);
;             PG8_WAIT_V(8); PG8_WAIT_L(0); PG8_BAR; PG8_MMA(0, 0, At, B0); PG8_MMA(0, 1, At, B1); PG8_BAR; PG8_SCHED;
;             PG8_LDA(At, 0, 1); PG8_STAGE(PG8_SB(0, 0), b2, voffB); PG8_STAGE(PG8_SB(0, 1), b2 + hstepB, voffB); PG8_STAGE(PG8_SA(0, 0), a2, voffA);
;             PG8_WAIT_V(8); PG8_WAIT_L(0); PG8_BAR; PG8_MMA(1, 0, At, B0); PG8_MMA(1, 1, At, B1); PG8_BAR; PG8_SCHED;
.LBB0_1007:
	ds_read_b128 v[128:131], v176
	ds_read_b128 v[132:135], v176 offset:1024
	ds_read_b128 v[136:139], v176 offset:2048
	ds_read_b128 v[140:143], v176 offset:3072
	ds_read_b128 v[162:165], v177
	ds_read_b128 v[166:169], v177 offset:1024
	ds_read_b128 v[170:173], v177 offset:2048
	ds_read_b128 v[180:183], v177 offset:3072
	s_add_u32 s36, s34, 0xfffc0080
	s_addc_u32 s37, s35, -1
	s_cmp_eq_u32 s56, 12
	s_cselect_b32 s39, s25, s37
	s_cselect_b32 s38, s52, s36
	s_cselect_b32 s37, s23, s55
	s_cselect_b32 s36, s53, s54
	s_add_i32 m0, s41, 0xc000
	ds_read_b128 v[186:189], v178
	ds_read_b128 v[190:193], v178 offset:1024
	ds_read_b128 v[194:197], v178 offset:2048
	ds_read_b128 v[198:201], v178 offset:3072
	ds_read_b128 v[202:205], v178 offset:4096
	ds_read_b128 v[206:209], v178 offset:5120
	ds_read_b128 v[210:213], v178 offset:6144
	ds_read_b128 v[214:217], v178 offset:7168
	global_load_lds_dwordx4 v154, s[34:35]
	s_add_i32 m0, s41, 0xe000
	s_nop 0
	global_load_lds_dwordx4 v156, s[34:35]
	s_waitcnt vmcnt(8) lgkmcnt(0)
	s_setprio 1
	s_barrier
	v_mfma_f32_16x16x32_bf16 v[124:127], v[128:131], v[186:189], v[124:127]
	v_mfma_f32_16x16x32_bf16 v[120:123], v[136:139], v[186:189], v[120:123]
	v_mfma_f32_16x16x32_bf16 v[108:111], v[128:131], v[194:197], v[108:111]
	v_mfma_f32_16x16x32_bf16 v[104:107], v[136:139], v[194:197], v[104:107]
	v_mfma_f32_16x16x32_bf16 v[92:95], v[128:131], v[202:205], v[92:95]
	v_mfma_f32_16x16x32_bf16 v[88:91], v[136:139], v[202:205], v[88:91]
	v_mfma_f32_16x16x32_bf16 v[76:79], v[128:131], v[210:213], v[76:79]
	v_mfma_f32_16x16x32_bf16 v[72:75], v[136:139], v[210:213], v[72:75]
	v_mfma_f32_16x16x32_bf16 v[124:127], v[132:135], v[190:193], v[124:127]
	v_mfma_f32_16x16x32_bf16 v[120:123], v[140:143], v[190:193], v[120:123]
	v_mfma_f32_16x16x32_bf16 v[108:111], v[132:135], v[198:201], v[108:111]
	v_mfma_f32_16x16x32_bf16 v[104:107], v[140:143], v[198:201], v[104:107]
	v_mfma_f32_16x16x32_bf16 v[92:95], v[132:135], v[206:209], v[92:95]
	v_mfma_f32_16x16x32_bf16 v[88:91], v[140:143], v[206:209], v[88:91]
	v_mfma_f32_16x16x32_bf16 v[76:79], v[132:135], v[214:217], v[76:79]
	v_mfma_f32_16x16x32_bf16 v[72:75], v[140:143], v[214:217], v[72:75]
	v_mfma_f32_16x16x32_bf16 v[116:119], v[162:165], v[186:189], v[116:119]
	v_mfma_f32_16x16x32_bf16 v[112:115], v[170:173], v[186:189], v[112:115]
	v_mfma_f32_16x16x32_bf16 v[100:103], v[162:165], v[194:197], v[100:103]
	v_mfma_f32_16x16x32_bf16 v[96:99], v[170:173], v[194:197], v[96:99]
	v_mfma_f32_16x16x32_bf16 v[84:87], v[162:165], v[202:205], v[84:87]
	v_mfma_f32_16x16x32_bf16 v[80:83], v[170:173], v[202:205], v[80:83]
	v_mfma_f32_16x16x32_bf16 v[68:71], v[162:165], v[210:213], v[68:71]
	v_mfma_f32_16x16x32_bf16 v[64:67], v[170:173], v[210:213], v[64:67]
	v_mfma_f32_16x16x32_bf16 v[116:119], v[166:169], v[190:193], v[116:119]
	v_mfma_f32_16x16x32_bf16 v[112:115], v[180:183], v[190:193], v[112:115]
	v_mfma_f32_16x16x32_bf16 v[100:103], v[166:169], v[198:201], v[100:103]
	v_mfma_f32_16x16x32_bf16 v[96:99], v[180:183], v[198:201], v[96:99]
	v_mfma_f32_16x16x32_bf16 v[84:87], v[166:169], v[206:209], v[84:87]
	v_mfma_f32_16x16x32_bf16 v[80:83], v[180:183], v[206:209], v[80:83]
	v_mfma_f32_16x16x32_bf16 v[68:71], v[166:169], v[214:217], v[68:71]
	v_mfma_f32_16x16x32_bf16 v[64:67], v[180:183], v[214:217], v[64:67]
	s_setprio 0
	s_barrier
	s_add_i32 s57, s48, s40
	s_mov_b32 m0, s57
	ds_read_b128 v[186:189], v178 offset:16384
	ds_read_b128 v[190:193], v178 offset:17408
	ds_read_b128 v[194:197], v178 offset:18432
	ds_read_b128 v[198:201], v178 offset:19456
	ds_read_b128 v[202:205], v178 offset:20480
	ds_read_b128 v[206:209], v178 offset:21504
	ds_read_b128 v[210:213], v178 offset:22528
	ds_read_b128 v[214:217], v178 offset:23552
	global_load_lds_dwordx4 v146, s[36:37]
	s_add_i32 m0, s57, 0x2000
	s_add_u32 s58, s36, 0x40000
	s_addc_u32 s59, s37, 0
	s_add_u32 s80, s38, s12
	s_addc_u32 s81, s39, s13
	s_add_i32 s57, s49, s40
	global_load_lds_dwordx4 v150, s[36:37]
	s_mov_b32 m0, s57
	s_nop 0
	global_load_lds_dwordx4 v146, s[58:59]
	s_add_i32 m0, s57, 0x2000
	s_nop 0
	global_load_lds_dwordx4 v150, s[58:59]
	s_mov_b32 m0, s41
	s_nop 0
	global_load_lds_dwordx4 v144, s[38:39]
	s_mov_b32 m0, s42
	s_nop 0
	global_load_lds_dwordx4 v148, s[38:39]
	s_waitcnt vmcnt(8) lgkmcnt(0)
	s_setprio 1
	s_barrier
	v_mfma_f32_16x16x32_bf16 v[60:63], v[128:131], v[186:189], v[60:63]
	v_mfma_f32_16x16x32_bf16 v[56:59], v[136:139], v[186:189], v[56:59]
	v_mfma_f32_16x16x32_bf16 v[44:47], v[128:131], v[194:197], v[44:47]
	v_mfma_f32_16x16x32_bf16 v[40:43], v[136:139], v[194:197], v[40:43]
	v_mfma_f32_16x16x32_bf16 v[28:31], v[128:131], v[202:205], v[28:31]
	v_mfma_f32_16x16x32_bf16 v[24:27], v[136:139], v[202:205], v[24:27]
	v_mfma_f32_16x16x32_bf16 v[12:15], v[128:131], v[210:213], v[12:15]
	v_mfma_f32_16x16x32_bf16 v[8:11], v[136:139], v[210:213], v[8:11]
	v_mfma_f32_16x16x32_bf16 v[60:63], v[132:135], v[190:193], v[60:63]
	v_mfma_f32_16x16x32_bf16 v[56:59], v[140:143], v[190:193], v[56:59]
	v_mfma_f32_16x16x32_bf16 v[44:47], v[132:135], v[198:201], v[44:47]
	v_mfma_f32_16x16x32_bf16 v[40:43], v[140:143], v[198:201], v[40:43]
	v_mfma_f32_16x16x32_bf16 v[28:31], v[132:135], v[206:209], v[28:31]
	v_mfma_f32_16x16x32_bf16 v[24:27], v[140:143], v[206:209], v[24:27]
	v_mfma_f32_16x16x32_bf16 v[12:15], v[132:135], v[214:217], v[12:15]
	v_mfma_f32_16x16x32_bf16 v[8:11], v[140:143], v[214:217], v[8:11]
	v_mfma_f32_16x16x32_bf16 v[52:55], v[162:165], v[186:189], v[52:55]
	v_mfma_f32_16x16x32_bf16 v[48:51], v[170:173], v[186:189], v[48:51]
	v_mfma_f32_16x16x32_bf16 v[36:39], v[162:165], v[194:197], v[36:39]
	v_mfma_f32_16x16x32_bf16 v[32:35], v[170:173], v[194:197], v[32:35]
	v_mfma_f32_16x16x32_bf16 v[20:23], v[162:165], v[202:205], v[20:23]
	v_mfma_f32_16x16x32_bf16 v[16:19], v[170:173], v[202:205], v[16:19]
	v_mfma_f32_16x16x32_bf16 v[4:7], v[162:165], v[210:213], v[4:7]
	v_mfma_f32_16x16x32_bf16 v[0:3], v[170:173], v[210:213], v[0:3]
	v_mfma_f32_16x16x32_bf16 v[52:55], v[166:169], v[190:193], v[52:55]
	v_mfma_f32_16x16x32_bf16 v[48:51], v[180:183], v[190:193], v[48:51]
	v_mfma_f32_16x16x32_bf16 v[36:39], v[166:169], v[198:201], v[36:39]
	v_mfma_f32_16x16x32_bf16 v[32:35], v[180:183], v[198:201], v[32:35]
	v_mfma_f32_16x16x32_bf16 v[20:23], v[166:169], v[206:209], v[20:23]
	v_mfma_f32_16x16x32_bf16 v[16:19], v[180:183], v[206:209], v[16:19]
	v_mfma_f32_16x16x32_bf16 v[4:7], v[166:169], v[214:217], v[4:7]
	v_mfma_f32_16x16x32_bf16 v[0:3], v[180:183], v[214:217], v[0:3]
	s_setprio 0
	s_barrier
; #define PG8_STAGE(bufoff, gbase, voff) do { _Pragma("unroll") for (int _i = 0; _i < 2; ++_i) \
;         __builtin_amdgcn_global_load_lds((const unsigned*)((const char*)(gbase) + (voff)[_i]), (PG8_LAS unsigned*)(lds + (bufoff) + ldsw + _i * 8192), 16, 0, 0); } while (0)
; #define PG8_LDA(dst, b, h) do { _Pragma("unroll") for (int m = 0; m < 4; ++m) _Pragma("unroll") for (int k = 0; k < 2; ++k) dst[m][k] = *(const PG8_LAS bf16x8*)(lds + PG8_SA(b, h) + aoff + m * 2048 + k * 1024); } while (0)
; #define PG8_LDB(dst, b, h) do { _Pragma("unroll") for (int n = 0; n < 2; ++n) _Pragma("unroll") for (int k = 0; k < 2; ++k) dst[n][k] = *(const PG8_LAS bf16x8*)(lds + PG8_SB(b, h) + boff + n * 2048 + k * 1024); } while (0)
; #define PG8_MMA(ai, bj, At, Bt) do { __builtin_amdgcn_s_setprio(1); _Pragma("unroll") for (int m = 0; m < 4; ++m) _Pragma("unroll") for (int n = 0; n < 2; ++n) _Pragma("unroll") for (int k = 0; k < 2; ++k) \
;         acc[ai][bj][m][n] = __builtin_amdgcn_mfma_f32_16x16x32_bf16(Bt[n][k], At[m][k], acc[ai][bj][m][n], 0, 0, 0); __builtin_amdgcn_s_setprio(0); } while (0)
; #define PG8_WAIT_V(n) asm volatile("s_waitcnt vmcnt(" #n ")" ::: "memory")
; #define PG8_WAIT_L(n) asm volatile("s_waitcnt lgkmcnt(" #n ")" ::: "memory")
; #define PG8_BAR __builtin_amdgcn_s_barrier()
; #define PG8_SCHED __builtin_amdgcn_sched_barrier(0)
; template <class Epi, class Sched, bool ALIGN_EPI = false, bool SP2 = false>
; __device__ __forceinline__ void gemm_phase(PG8_LAS unsigned char* lds, const Gemm g, const Sched& S, const Epi& E) {
;     ...
;             PG8_LDB(B0, 1, 0); PG8_LDB(B1, 1, 1); PG8_SCHED; PG8_LDA(At, 1, 0); PG8_STAGE(PG8_SA(0, 1), a2 + hstepA, voffA);
;             PG8_WAIT_V(8); PG8_WAIT_L(0); PG8_BAR; PG8_MMA(0, 0, At, B0); PG8_MMA(0, 1, At, B1); PG8_BAR; PG8_SCHED;
;             PG8_LDA(At, 1, 1); PG8_STAGE(PG8_SB(1, 0), b3, voffB); PG8_STAGE(PG8_SB(1, 1), b3 + hstepB, voffB); PG8_STAGE(PG8_SA(1, 0), a3, voffA);
;             PG8_WAIT_V(8); PG8_WAIT_L(0); PG8_BAR; PG8_MMA(1, 0, At, B0); PG8_MMA(1, 1, At, B1); PG8_BAR; PG8_SCHED;
;     ...
;         if constexpr (ALIGN_EPI) { if (wr == 0) PG8_BAR; }
	s_add_i32 s57, 0, 0x18000
	s_add_i32 s58, 0, 0x1c000
	v_add_u32_e32 v140, s57, v175
	v_add_u32_e32 v179, s58, v175
	ds_read_b128 v[128:131], v140
	ds_read_b128 v[132:135], v140 offset:1024
	ds_read_b128 v[136:139], v140 offset:2048
	ds_read_b128 v[140:143], v140 offset:3072
	ds_read_b128 v[162:165], v179
	ds_read_b128 v[166:169], v179 offset:1024
	ds_read_b128 v[170:173], v179 offset:2048
	ds_read_b128 v[180:183], v179 offset:3072
	s_add_u32 s38, s38, 0x40000
	s_addc_u32 s39, s39, 0
	s_mov_b32 m0, s43
	ds_read_b128 v[186:189], v178 offset:32768
	ds_read_b128 v[190:193], v178 offset:33792
	ds_read_b128 v[194:197], v178 offset:34816
	ds_read_b128 v[198:201], v178 offset:35840
	ds_read_b128 v[202:205], v178 offset:36864
	ds_read_b128 v[206:209], v178 offset:37888
	ds_read_b128 v[210:213], v178 offset:38912
	ds_read_b128 v[214:217], v178 offset:39936
	global_load_lds_dwordx4 v144, s[38:39]
	s_mov_b32 m0, s44
	s_nop 0
	global_load_lds_dwordx4 v148, s[38:39]
	s_waitcnt vmcnt(8) lgkmcnt(0)
	s_setprio 1
	s_barrier
	v_mfma_f32_16x16x32_bf16 v[124:127], v[128:131], v[186:189], v[124:127]
	v_mfma_f32_16x16x32_bf16 v[120:123], v[136:139], v[186:189], v[120:123]
	v_mfma_f32_16x16x32_bf16 v[108:111], v[128:131], v[194:197], v[108:111]
	v_mfma_f32_16x16x32_bf16 v[104:107], v[136:139], v[194:197], v[104:107]
	v_mfma_f32_16x16x32_bf16 v[92:95], v[128:131], v[202:205], v[92:95]
	v_mfma_f32_16x16x32_bf16 v[88:91], v[136:139], v[202:205], v[88:91]
	v_mfma_f32_16x16x32_bf16 v[76:79], v[128:131], v[210:213], v[76:79]
	v_mfma_f32_16x16x32_bf16 v[72:75], v[136:139], v[210:213], v[72:75]
	v_mfma_f32_16x16x32_bf16 v[124:127], v[132:135], v[190:193], v[124:127]
	v_mfma_f32_16x16x32_bf16 v[120:123], v[140:143], v[190:193], v[120:123]
	v_mfma_f32_16x16x32_bf16 v[108:111], v[132:135], v[198:201], v[108:111]
	v_mfma_f32_16x16x32_bf16 v[104:107], v[140:143], v[198:201], v[104:107]
	v_mfma_f32_16x16x32_bf16 v[92:95], v[132:135], v[206:209], v[92:95]
	v_mfma_f32_16x16x32_bf16 v[88:91], v[140:143], v[206:209], v[88:91]
	v_mfma_f32_16x16x32_bf16 v[76:79], v[132:135], v[214:217], v[76:79]
	v_mfma_f32_16x16x32_bf16 v[72:75], v[140:143], v[214:217], v[72:75]
	v_mfma_f32_16x16x32_bf16 v[116:119], v[162:165], v[186:189], v[116:119]
	v_mfma_f32_16x16x32_bf16 v[112:115], v[170:173], v[186:189], v[112:115]
	v_mfma_f32_16x16x32_bf16 v[100:103], v[162:165], v[194:197], v[100:103]
	v_mfma_f32_16x16x32_bf16 v[96:99], v[170:173], v[194:197], v[96:99]
	v_mfma_f32_16x16x32_bf16 v[84:87], v[162:165], v[202:205], v[84:87]
	v_mfma_f32_16x16x32_bf16 v[80:83], v[170:173], v[202:205], v[80:83]
	v_mfma_f32_16x16x32_bf16 v[68:71], v[162:165], v[210:213], v[68:71]
	v_mfma_f32_16x16x32_bf16 v[64:67], v[170:173], v[210:213], v[64:67]
	v_mfma_f32_16x16x32_bf16 v[116:119], v[166:169], v[190:193], v[116:119]
	v_mfma_f32_16x16x32_bf16 v[112:115], v[180:183], v[190:193], v[112:115]
	v_mfma_f32_16x16x32_bf16 v[100:103], v[166:169], v[198:201], v[100:103]
	v_mfma_f32_16x16x32_bf16 v[96:99], v[180:183], v[198:201], v[96:99]
	v_mfma_f32_16x16x32_bf16 v[84:87], v[166:169], v[206:209], v[84:87]
	v_mfma_f32_16x16x32_bf16 v[80:83], v[180:183], v[206:209], v[80:83]
	v_mfma_f32_16x16x32_bf16 v[68:71], v[166:169], v[214:217], v[68:71]
	v_mfma_f32_16x16x32_bf16 v[64:67], v[180:183], v[214:217], v[64:67]
	s_setprio 0
	s_barrier
	s_add_i32 s38, s57, s40
	s_add_u32 s82, s36, s12
	s_addc_u32 s83, s37, s13
	s_mov_b32 m0, s38
	ds_read_b128 v[186:189], v178 offset:49152
	ds_read_b128 v[190:193], v178 offset:50176
	ds_read_b128 v[194:197], v178 offset:51200
	ds_read_b128 v[198:201], v178 offset:52224
	ds_read_b128 v[202:205], v178 offset:53248
	ds_read_b128 v[206:209], v178 offset:54272
	ds_read_b128 v[210:213], v178 offset:55296
	ds_read_b128 v[214:217], v178 offset:56320
	global_load_lds_dwordx4 v146, s[82:83]
	s_add_i32 m0, s38, 0x2000
	s_add_u32 s36, s36, 0x40080
	s_addc_u32 s37, s37, 0
	s_add_i32 s38, s58, s40
	global_load_lds_dwordx4 v150, s[82:83]
	s_mov_b32 m0, s38
	s_nop 0
	global_load_lds_dwordx4 v146, s[36:37]
	s_add_i32 m0, s38, 0x2000
	s_nop 0
	global_load_lds_dwordx4 v150, s[36:37]
	s_mov_b32 m0, s45
	s_nop 0
	global_load_lds_dwordx4 v144, s[80:81]
	s_mov_b32 m0, s46
	s_nop 0
	global_load_lds_dwordx4 v148, s[80:81]
	s_waitcnt vmcnt(8) lgkmcnt(0)
	s_setprio 1
	s_barrier
	v_mfma_f32_16x16x32_bf16 v[60:63], v[128:131], v[186:189], v[60:63]
	v_mfma_f32_16x16x32_bf16 v[56:59], v[136:139], v[186:189], v[56:59]
	v_mfma_f32_16x16x32_bf16 v[44:47], v[128:131], v[194:197], v[44:47]
	v_mfma_f32_16x16x32_bf16 v[40:43], v[136:139], v[194:197], v[40:43]
	v_mfma_f32_16x16x32_bf16 v[28:31], v[128:131], v[202:205], v[28:31]
	v_mfma_f32_16x16x32_bf16 v[24:27], v[136:139], v[202:205], v[24:27]
	v_mfma_f32_16x16x32_bf16 v[12:15], v[128:131], v[210:213], v[12:15]
	v_mfma_f32_16x16x32_bf16 v[8:11], v[136:139], v[210:213], v[8:11]
	v_mfma_f32_16x16x32_bf16 v[60:63], v[132:135], v[190:193], v[60:63]
	v_mfma_f32_16x16x32_bf16 v[56:59], v[140:143], v[190:193], v[56:59]
	v_mfma_f32_16x16x32_bf16 v[44:47], v[132:135], v[198:201], v[44:47]
	v_mfma_f32_16x16x32_bf16 v[40:43], v[140:143], v[198:201], v[40:43]
	v_mfma_f32_16x16x32_bf16 v[28:31], v[132:135], v[206:209], v[28:31]
	v_mfma_f32_16x16x32_bf16 v[24:27], v[140:143], v[206:209], v[24:27]
	v_mfma_f32_16x16x32_bf16 v[12:15], v[132:135], v[214:217], v[12:15]
	v_mfma_f32_16x16x32_bf16 v[8:11], v[140:143], v[214:217], v[8:11]
	v_mfma_f32_16x16x32_bf16 v[52:55], v[162:165], v[186:189], v[52:55]
	v_mfma_f32_16x16x32_bf16 v[48:51], v[170:173], v[186:189], v[48:51]
	v_mfma_f32_16x16x32_bf16 v[36:39], v[162:165], v[194:197], v[36:39]
	v_mfma_f32_16x16x32_bf16 v[32:35], v[170:173], v[194:197], v[32:35]
	v_mfma_f32_16x16x32_bf16 v[20:23], v[162:165], v[202:205], v[20:23]
	v_mfma_f32_16x16x32_bf16 v[16:19], v[170:173], v[202:205], v[16:19]
	v_mfma_f32_16x16x32_bf16 v[4:7], v[162:165], v[210:213], v[4:7]
	v_mfma_f32_16x16x32_bf16 v[0:3], v[170:173], v[210:213], v[0:3]
	v_mfma_f32_16x16x32_bf16 v[52:55], v[166:169], v[190:193], v[52:55]
	v_mfma_f32_16x16x32_bf16 v[48:51], v[180:183], v[190:193], v[48:51]
	v_mfma_f32_16x16x32_bf16 v[36:39], v[166:169], v[198:201], v[36:39]
	v_mfma_f32_16x16x32_bf16 v[32:35], v[180:183], v[198:201], v[32:35]
	v_mfma_f32_16x16x32_bf16 v[20:23], v[166:169], v[206:209], v[20:23]
	v_mfma_f32_16x16x32_bf16 v[16:19], v[180:183], v[206:209], v[16:19]
	v_mfma_f32_16x16x32_bf16 v[4:7], v[166:169], v[214:217], v[4:7]
	v_mfma_f32_16x16x32_bf16 v[0:3], v[180:183], v[214:217], v[0:3]
	s_setprio 0
	s_barrier
	s_add_i32 s56, s56, 2
	s_add_u32 s34, s34, 0x100
	s_addc_u32 s35, s35, 0
	s_add_u32 s54, s54, 0x100
	s_addc_u32 s55, s55, 0
	s_cmp_gt_u32 s56, 13
	s_cbranch_scc0 .LBB0_1007
	s_and_b64 vcc, exec, s[16:17]
	s_cbranch_vccz .LBB0_1010
	s_barrier

; #define PG8_STAGE(bufoff, gbase, voff) do { _Pragma("unroll") for (int _i = 0; _i < 2; ++_i) \
;         __builtin_amdgcn_global_load_lds((const unsigned*)((const char*)(gbase) + (voff)[_i]), (PG8_LAS unsigned*)(lds + (bufoff) + ldsw + _i * 8192), 16, 0, 0); } while (0)
; #define PG8_LDA(dst, b, h) do { _Pragma("unroll") for (int m = 0; m < 4; ++m) _Pragma("unroll") for (int k = 0; k < 2; ++k) dst[m][k] = *(const PG8_LAS bf16x8*)(lds + PG8_SA(b, h) + aoff + m * 2048 + k * 1024); } while (0)
; #define PG8_LDB(dst, b, h) do { _Pragma("unroll") for (int n = 0; n < 2; ++n) _Pragma("unroll") for (int k = 0; k < 2; ++k) dst[n][k] = *(const PG8_LAS bf16x8*)(lds + PG8_SB(b, h) + boff + n * 2048 + k * 1024); } while (0)
; #define PG8_MMA(ai, bj, At, Bt) do { __builtin_amdgcn_s_setprio(1); _Pragma("unroll") for (int m = 0; m < 4; ++m) _Pragma("unroll") for (int n = 0; n < 2; ++n) _Pragma("unroll") for (int k = 0; k < 2; ++k) \
;         acc[ai][bj][m][n] = __builtin_amdgcn_mfma_f32_16x16x32_bf16(Bt[n][k], At[m][k], acc[ai][bj][m][n], 0, 0, 0); __builtin_amdgcn_s_setprio(0); } while (0)
; #define PG8_WAIT_V(n) asm volatile("s_waitcnt vmcnt(" #n ")" ::: "memory")
; #define PG8_WAIT_L(n) asm volatile("s_waitcnt lgkmcnt(" #n ")" ::: "memory")
; #define PG8_BAR __builtin_amdgcn_s_barrier()
; #define PG8_SCHED __builtin_amdgcn_sched_barrier(0)
; template <class Epi, class Sched, bool ALIGN_EPI = false, bool SP2 = false>
; __device__ __forceinline__ void gemm_phase(PG8_LAS unsigned char* lds, const Gemm g, const Sched& S, const Epi& E) {
;     ...
;             PG8_LDB(B0, 0, 0); PG8_LDB(B1, 0, 1); PG8_SCHED; PG8_LDA(At, 0, 0); PG8_STAGE(PG8_SA(1, 1), a1 + hstepA, voffA);
;             PG8_WAIT_V(8); PG8_WAIT_L(0); PG8_BAR; PG8_MMA(0, 0, At, B0); PG8_MMA(0, 1, At, B1); PG8_BAR; PG8_SCHED;
;             PG8_LDA(At, 0, 1); PG8_STAGE(PG8_SB(0, 0), b2, voffB); PG8_STAGE(PG8_SB(0, 1), b2 + hstepB, voffB); PG8_STAGE(PG8_SA(0, 0), a2, voffA);
;             PG8_WAIT_V(8); PG8_WAIT_L(0); PG8_BAR; PG8_MMA(1, 0, At, B0); PG8_MMA(1, 1, At, B1); PG8_BAR; PG8_SCHED;
.LBB0_1061:
	ds_read_b128 v[128:131], v199
	ds_read_b128 v[132:135], v199 offset:1024
	ds_read_b128 v[136:139], v199 offset:2048
	ds_read_b128 v[140:143], v199 offset:3072
	ds_read_b128 v[144:147], v200
	ds_read_b128 v[148:151], v200 offset:1024
	ds_read_b128 v[152:155], v200 offset:2048
	ds_read_b128 v[156:159], v200 offset:3072
	s_add_u32 s20, s18, 0xfff00080
	s_addc_u32 s21, s19, -1
	s_cmp_eq_u32 s45, 60
	s_cselect_b32 s23, s11, s21
	s_cselect_b32 s22, s41, s20
	s_cselect_b32 s21, s9, s44
	s_cselect_b32 s20, s42, s43
	v_lshl_add_u64 v[196:197], s[18:19], 0, v[180:181]
	s_add_i32 m0, s17, 0xc000
	ds_read_b128 v[160:163], v201
	ds_read_b128 v[164:167], v201 offset:1024
	ds_read_b128 v[188:191], v201 offset:2048
	ds_read_b128 v[192:195], v201 offset:3072
	ds_read_b128 v[202:205], v201 offset:4096
	ds_read_b128 v[206:209], v201 offset:5120
	ds_read_b128 v[210:213], v201 offset:6144
	ds_read_b128 v[214:217], v201 offset:7168
	global_load_lds_dwordx4 v[196:197], off
	v_lshl_add_u64 v[196:197], s[18:19], 0, v[182:183]
	s_add_i32 m0, s17, 0xe000
	s_nop 0
	global_load_lds_dwordx4 v[196:197], off
	s_waitcnt vmcnt(8) lgkmcnt(0)
	s_setprio 1
	s_barrier
	v_mfma_f32_16x16x32_bf16 v[124:127], v[128:131], v[160:163], v[124:127]
	v_mfma_f32_16x16x32_bf16 v[120:123], v[136:139], v[160:163], v[120:123]
	v_mfma_f32_16x16x32_bf16 v[112:115], v[128:131], v[188:191], v[112:115]
	v_mfma_f32_16x16x32_bf16 v[104:107], v[136:139], v[188:191], v[104:107]
	v_mfma_f32_16x16x32_bf16 v[96:99], v[128:131], v[202:205], v[96:99]
	v_mfma_f32_16x16x32_bf16 v[88:91], v[136:139], v[202:205], v[88:91]
	v_mfma_f32_16x16x32_bf16 v[80:83], v[128:131], v[210:213], v[80:83]
	v_mfma_f32_16x16x32_bf16 v[72:75], v[136:139], v[210:213], v[72:75]
	v_mfma_f32_16x16x32_bf16 v[124:127], v[132:135], v[164:167], v[124:127]
	v_mfma_f32_16x16x32_bf16 v[120:123], v[140:143], v[164:167], v[120:123]
	v_mfma_f32_16x16x32_bf16 v[112:115], v[132:135], v[192:195], v[112:115]
	v_mfma_f32_16x16x32_bf16 v[104:107], v[140:143], v[192:195], v[104:107]
	v_mfma_f32_16x16x32_bf16 v[96:99], v[132:135], v[206:209], v[96:99]
	v_mfma_f32_16x16x32_bf16 v[88:91], v[140:143], v[206:209], v[88:91]
	v_mfma_f32_16x16x32_bf16 v[80:83], v[132:135], v[214:217], v[80:83]
	v_mfma_f32_16x16x32_bf16 v[72:75], v[140:143], v[214:217], v[72:75]
	v_mfma_f32_16x16x32_bf16 v[116:119], v[144:147], v[160:163], v[116:119]
	v_mfma_f32_16x16x32_bf16 v[108:111], v[152:155], v[160:163], v[108:111]
	v_mfma_f32_16x16x32_bf16 v[100:103], v[144:147], v[188:191], v[100:103]
	v_mfma_f32_16x16x32_bf16 v[92:95], v[152:155], v[188:191], v[92:95]
	v_mfma_f32_16x16x32_bf16 v[84:87], v[144:147], v[202:205], v[84:87]
	v_mfma_f32_16x16x32_bf16 v[76:79], v[152:155], v[202:205], v[76:79]
	v_mfma_f32_16x16x32_bf16 v[68:71], v[144:147], v[210:213], v[68:71]
	v_mfma_f32_16x16x32_bf16 v[64:67], v[152:155], v[210:213], v[64:67]
	v_mfma_f32_16x16x32_bf16 v[116:119], v[148:151], v[164:167], v[116:119]
	v_mfma_f32_16x16x32_bf16 v[108:111], v[156:159], v[164:167], v[108:111]
	v_mfma_f32_16x16x32_bf16 v[100:103], v[148:151], v[192:195], v[100:103]
	v_mfma_f32_16x16x32_bf16 v[92:95], v[156:159], v[192:195], v[92:95]
	v_mfma_f32_16x16x32_bf16 v[84:87], v[148:151], v[206:209], v[84:87]
	v_mfma_f32_16x16x32_bf16 v[76:79], v[156:159], v[206:209], v[76:79]
	v_mfma_f32_16x16x32_bf16 v[68:71], v[148:151], v[214:217], v[68:71]
	v_mfma_f32_16x16x32_bf16 v[64:67], v[156:159], v[214:217], v[64:67]
	s_setprio 0
	s_barrier
	s_add_i32 s46, s38, s29
	v_lshl_add_u64 v[196:197], s[20:21], 0, v[170:171]
	s_mov_b32 m0, s46
	ds_read_b128 v[160:163], v201 offset:16384
	ds_read_b128 v[164:167], v201 offset:17408
	ds_read_b128 v[188:191], v201 offset:18432
	ds_read_b128 v[192:195], v201 offset:19456
	ds_read_b128 v[202:205], v201 offset:20480
	ds_read_b128 v[206:209], v201 offset:21504
	ds_read_b128 v[210:213], v201 offset:22528
	ds_read_b128 v[214:217], v201 offset:23552
	global_load_lds_dwordx4 v[196:197], off
	s_add_i32 m0, s46, 0x2000
	s_add_u32 s46, s20, 0x100000
	v_lshl_add_u64 v[218:219], s[20:21], 0, v[174:175]
	s_addc_u32 s47, s21, 0
	s_add_i32 s48, s39, s29
	global_load_lds_dwordx4 v[218:219], off
	v_lshl_add_u64 v[220:221], s[46:47], 0, v[170:171]
	s_mov_b32 m0, s48
	v_lshl_add_u64 v[222:223], s[22:23], 0, v[172:173]
	global_load_lds_dwordx4 v[220:221], off
	v_lshl_add_u64 v[220:221], s[46:47], 0, v[174:175]
	s_add_i32 m0, s48, 0x2000
	s_nop 0
	global_load_lds_dwordx4 v[220:221], off
	v_lshl_add_u64 v[220:221], s[22:23], 0, v[168:169]
	s_mov_b32 m0, s17
	s_nop 0
	global_load_lds_dwordx4 v[220:221], off
	s_mov_b32 m0, s30
	s_nop 0
	global_load_lds_dwordx4 v[222:223], off
	s_waitcnt vmcnt(8) lgkmcnt(0)
	s_setprio 1
	s_barrier
; #define PG8_STAGE(bufoff, gbase, voff) do { _Pragma("unroll") for (int _i = 0; _i < 2; ++_i) \
;         __builtin_amdgcn_global_load_lds((const unsigned*)((const char*)(gbase) + (voff)[_i]), (PG8_LAS unsigned*)(lds + (bufoff) + ldsw + _i * 8192), 16, 0, 0); } while (0)
; #define PG8_LDA(dst, b, h) do { _Pragma("unroll") for (int m = 0; m < 4; ++m) _Pragma("unroll") for (int k = 0; k < 2; ++k) dst[m][k] = *(const PG8_LAS bf16x8*)(lds + PG8_SA(b, h) + aoff + m * 2048 + k * 1024); } while (0)
; #define PG8_LDB(dst, b, h) do { _Pragma("unroll") for (int n = 0; n < 2; ++n) _Pragma("unroll") for (int k = 0; k < 2; ++k) dst[n][k] = *(const PG8_LAS bf16x8*)(lds + PG8_SB(b, h) + boff + n * 2048 + k * 1024); } while (0)
; #define PG8_MMA(ai, bj, At, Bt) do { __builtin_amdgcn_s_setprio(1); _Pragma("unroll") for (int m = 0; m < 4; ++m) _Pragma("unroll") for (int n = 0; n < 2; ++n) _Pragma("unroll") for (int k = 0; k < 2; ++k) \
;         acc[ai][bj][m][n] = __builtin_amdgcn_mfma_f32_16x16x32_bf16(Bt[n][k], At[m][k], acc[ai][bj][m][n], 0, 0, 0); __builtin_amdgcn_s_setprio(0); } while (0)
; #define PG8_WAIT_V(n) asm volatile("s_waitcnt vmcnt(" #n ")" ::: "memory")
; #define PG8_WAIT_L(n) asm volatile("s_waitcnt lgkmcnt(" #n ")" ::: "memory")
; #define PG8_BAR __builtin_amdgcn_s_barrier()
; #define PG8_SCHED __builtin_amdgcn_sched_barrier(0)
; template <class Epi, class Sched, bool ALIGN_EPI = false, bool SP2 = false>
; __device__ __forceinline__ void gemm_phase(PG8_LAS unsigned char* lds, const Gemm g, const Sched& S, const Epi& E) {
;     ...
;             PG8_WAIT_V(8); PG8_WAIT_L(0); PG8_BAR; PG8_MMA(1, 0, At, B0); PG8_MMA(1, 1, At, B1); PG8_BAR; PG8_SCHED;
;             PG8_LDB(B0, 1, 0); PG8_LDB(B1, 1, 1); PG8_SCHED; PG8_LDA(At, 1, 0); PG8_STAGE(PG8_SA(0, 1), a2 + hstepA, voffA);
;             PG8_WAIT_V(8); PG8_WAIT_L(0); PG8_BAR; PG8_MMA(0, 0, At, B0); PG8_MMA(0, 1, At, B1); PG8_BAR; PG8_SCHED;
;             PG8_LDA(At, 1, 1); PG8_STAGE(PG8_SB(1, 0), b3, voffB); PG8_STAGE(PG8_SB(1, 1), b3 + hstepB, voffB); PG8_STAGE(PG8_SA(1, 0), a3, voffA);
	v_mfma_f32_16x16x32_bf16 v[60:63], v[128:131], v[160:163], v[60:63]
	v_mfma_f32_16x16x32_bf16 v[56:59], v[136:139], v[160:163], v[56:59]
	v_mfma_f32_16x16x32_bf16 v[48:51], v[128:131], v[188:191], v[48:51]
	v_mfma_f32_16x16x32_bf16 v[40:43], v[136:139], v[188:191], v[40:43]
	v_mfma_f32_16x16x32_bf16 v[32:35], v[128:131], v[202:205], v[32:35]
	v_mfma_f32_16x16x32_bf16 v[24:27], v[136:139], v[202:205], v[24:27]
	v_mfma_f32_16x16x32_bf16 v[16:19], v[128:131], v[210:213], v[16:19]
	v_mfma_f32_16x16x32_bf16 v[8:11], v[136:139], v[210:213], v[8:11]
	v_mfma_f32_16x16x32_bf16 v[60:63], v[132:135], v[164:167], v[60:63]
	v_mfma_f32_16x16x32_bf16 v[56:59], v[140:143], v[164:167], v[56:59]
	v_mfma_f32_16x16x32_bf16 v[48:51], v[132:135], v[192:195], v[48:51]
	v_mfma_f32_16x16x32_bf16 v[40:43], v[140:143], v[192:195], v[40:43]
	v_mfma_f32_16x16x32_bf16 v[32:35], v[132:135], v[206:209], v[32:35]
	v_mfma_f32_16x16x32_bf16 v[24:27], v[140:143], v[206:209], v[24:27]
	v_mfma_f32_16x16x32_bf16 v[16:19], v[132:135], v[214:217], v[16:19]
	v_mfma_f32_16x16x32_bf16 v[8:11], v[140:143], v[214:217], v[8:11]
	v_mfma_f32_16x16x32_bf16 v[52:55], v[144:147], v[160:163], v[52:55]
	v_mfma_f32_16x16x32_bf16 v[44:47], v[152:155], v[160:163], v[44:47]
	v_mfma_f32_16x16x32_bf16 v[36:39], v[144:147], v[188:191], v[36:39]
	v_mfma_f32_16x16x32_bf16 v[28:31], v[152:155], v[188:191], v[28:31]
	v_mfma_f32_16x16x32_bf16 v[20:23], v[144:147], v[202:205], v[20:23]
	v_mfma_f32_16x16x32_bf16 v[12:15], v[152:155], v[202:205], v[12:15]
	v_mfma_f32_16x16x32_bf16 v[4:7], v[144:147], v[210:213], v[4:7]
	v_mfma_f32_16x16x32_bf16 v[0:3], v[152:155], v[210:213], v[0:3]
	v_mfma_f32_16x16x32_bf16 v[52:55], v[148:151], v[164:167], v[52:55]
	v_mfma_f32_16x16x32_bf16 v[44:47], v[156:159], v[164:167], v[44:47]
	v_mfma_f32_16x16x32_bf16 v[36:39], v[148:151], v[192:195], v[36:39]
	v_mfma_f32_16x16x32_bf16 v[28:31], v[156:159], v[192:195], v[28:31]
	v_mfma_f32_16x16x32_bf16 v[20:23], v[148:151], v[206:209], v[20:23]
	v_mfma_f32_16x16x32_bf16 v[12:15], v[156:159], v[206:209], v[12:15]
	v_mfma_f32_16x16x32_bf16 v[4:7], v[148:151], v[214:217], v[4:7]
	v_mfma_f32_16x16x32_bf16 v[0:3], v[156:159], v[214:217], v[0:3]
	s_setprio 0
	s_barrier
	s_add_i32 s46, 0, 0x18000
	s_add_i32 s47, 0, 0x1c000
	v_add_u32_e32 v140, s46, v198
	v_add_u32_e32 v156, s47, v198
	ds_read_b128 v[128:131], v140
	ds_read_b128 v[132:135], v140 offset:1024
	ds_read_b128 v[136:139], v140 offset:2048
	ds_read_b128 v[140:143], v140 offset:3072
	ds_read_b128 v[144:147], v156
	ds_read_b128 v[148:151], v156 offset:1024
	ds_read_b128 v[152:155], v156 offset:2048
	ds_read_b128 v[156:159], v156 offset:3072
	s_add_u32 s22, s22, 0x100000
	s_addc_u32 s23, s23, 0
	s_mov_b32 m0, s31
	v_lshl_add_u64 v[224:225], s[22:23], 0, v[168:169]
	ds_read_b128 v[160:163], v201 offset:32768
	ds_read_b128 v[164:167], v201 offset:33792
	ds_read_b128 v[188:191], v201 offset:34816
	ds_read_b128 v[192:195], v201 offset:35840
	ds_read_b128 v[202:205], v201 offset:36864
	ds_read_b128 v[206:209], v201 offset:37888
	ds_read_b128 v[210:213], v201 offset:38912
	ds_read_b128 v[214:217], v201 offset:39936
	global_load_lds_dwordx4 v[224:225], off
	v_lshl_add_u64 v[224:225], s[22:23], 0, v[172:173]
	s_mov_b32 m0, s33
	s_nop 0
	global_load_lds_dwordx4 v[224:225], off
	s_waitcnt vmcnt(8) lgkmcnt(0)
	s_setprio 1
	s_barrier
	v_mfma_f32_16x16x32_bf16 v[124:127], v[128:131], v[160:163], v[124:127]
	v_mfma_f32_16x16x32_bf16 v[120:123], v[136:139], v[160:163], v[120:123]
	v_mfma_f32_16x16x32_bf16 v[112:115], v[128:131], v[188:191], v[112:115]
	v_mfma_f32_16x16x32_bf16 v[104:107], v[136:139], v[188:191], v[104:107]
	v_mfma_f32_16x16x32_bf16 v[96:99], v[128:131], v[202:205], v[96:99]
	v_mfma_f32_16x16x32_bf16 v[88:91], v[136:139], v[202:205], v[88:91]
	v_mfma_f32_16x16x32_bf16 v[80:83], v[128:131], v[210:213], v[80:83]
	v_mfma_f32_16x16x32_bf16 v[72:75], v[136:139], v[210:213], v[72:75]
	v_mfma_f32_16x16x32_bf16 v[124:127], v[132:135], v[164:167], v[124:127]
	v_mfma_f32_16x16x32_bf16 v[120:123], v[140:143], v[164:167], v[120:123]
	v_mfma_f32_16x16x32_bf16 v[112:115], v[132:135], v[192:195], v[112:115]
	v_mfma_f32_16x16x32_bf16 v[104:107], v[140:143], v[192:195], v[104:107]
	v_mfma_f32_16x16x32_bf16 v[96:99], v[132:135], v[206:209], v[96:99]
	v_mfma_f32_16x16x32_bf16 v[88:91], v[140:143], v[206:209], v[88:91]
	v_mfma_f32_16x16x32_bf16 v[80:83], v[132:135], v[214:217], v[80:83]
	v_mfma_f32_16x16x32_bf16 v[72:75], v[140:143], v[214:217], v[72:75]
	v_mfma_f32_16x16x32_bf16 v[116:119], v[144:147], v[160:163], v[116:119]
	v_mfma_f32_16x16x32_bf16 v[108:111], v[152:155], v[160:163], v[108:111]
	v_mfma_f32_16x16x32_bf16 v[100:103], v[144:147], v[188:191], v[100:103]
	v_mfma_f32_16x16x32_bf16 v[92:95], v[152:155], v[188:191], v[92:95]
	v_mfma_f32_16x16x32_bf16 v[84:87], v[144:147], v[202:205], v[84:87]
	v_mfma_f32_16x16x32_bf16 v[76:79], v[152:155], v[202:205], v[76:79]
	v_mfma_f32_16x16x32_bf16 v[68:71], v[144:147], v[210:213], v[68:71]
	v_mfma_f32_16x16x32_bf16 v[64:67], v[152:155], v[210:213], v[64:67]
	v_mfma_f32_16x16x32_bf16 v[116:119], v[148:151], v[164:167], v[116:119]
	v_mfma_f32_16x16x32_bf16 v[108:111], v[156:159], v[164:167], v[108:111]
	v_mfma_f32_16x16x32_bf16 v[100:103], v[148:151], v[192:195], v[100:103]
	v_mfma_f32_16x16x32_bf16 v[92:95], v[156:159], v[192:195], v[92:95]
	v_mfma_f32_16x16x32_bf16 v[84:87], v[148:151], v[206:209], v[84:87]
	v_mfma_f32_16x16x32_bf16 v[76:79], v[156:159], v[206:209], v[76:79]
	v_mfma_f32_16x16x32_bf16 v[68:71], v[148:151], v[214:217], v[68:71]
	v_mfma_f32_16x16x32_bf16 v[64:67], v[156:159], v[214:217], v[64:67]
	s_setprio 0
	s_barrier
; #define PG8_STAGE(bufoff, gbase, voff) do { _Pragma("unroll") for (int _i = 0; _i < 2; ++_i) \
;         __builtin_amdgcn_global_load_lds((const unsigned*)((const char*)(gbase) + (voff)[_i]), (PG8_LAS unsigned*)(lds + (bufoff) + ldsw + _i * 8192), 16, 0, 0); } while (0)
; #define PG8_LDA(dst, b, h) do { _Pragma("unroll") for (int m = 0; m < 4; ++m) _Pragma("unroll") for (int k = 0; k < 2; ++k) dst[m][k] = *(const PG8_LAS bf16x8*)(lds + PG8_SA(b, h) + aoff + m * 2048 + k * 1024); } while (0)
; #define PG8_MMA(ai, bj, At, Bt) do { __builtin_amdgcn_s_setprio(1); _Pragma("unroll") for (int m = 0; m < 4; ++m) _Pragma("unroll") for (int n = 0; n < 2; ++n) _Pragma("unroll") for (int k = 0; k < 2; ++k) \
;         acc[ai][bj][m][n] = __builtin_amdgcn_mfma_f32_16x16x32_bf16(Bt[n][k], At[m][k], acc[ai][bj][m][n], 0, 0, 0); __builtin_amdgcn_s_setprio(0); } while (0)
; #define PG8_WAIT_V(n) asm volatile("s_waitcnt vmcnt(" #n ")" ::: "memory")
; #define PG8_WAIT_L(n) asm volatile("s_waitcnt lgkmcnt(" #n ")" ::: "memory")
; #define PG8_BAR __builtin_amdgcn_s_barrier()
; #define PG8_SCHED __builtin_amdgcn_sched_barrier(0)
; template <class Epi, class Sched, bool ALIGN_EPI = false, bool SP2 = false>
; __device__ __forceinline__ void gemm_phase(PG8_LAS unsigned char* lds, const Gemm g, const Sched& S, const Epi& E) {
;     ...
;             PG8_LDA(At, 1, 1); PG8_STAGE(PG8_SB(1, 0), b3, voffB); PG8_STAGE(PG8_SB(1, 1), b3 + hstepB, voffB); PG8_STAGE(PG8_SA(1, 0), a3, voffA);
;             PG8_WAIT_V(8); PG8_WAIT_L(0); PG8_BAR; PG8_MMA(1, 0, At, B0); PG8_MMA(1, 1, At, B1); PG8_BAR; PG8_SCHED;
;     ...
;         if constexpr (ALIGN_EPI) { if (wr == 0) PG8_BAR; }
	s_add_i32 s22, s46, s29
	v_lshl_add_u64 v[196:197], v[196:197], 0, s[4:5]
	s_mov_b32 m0, s22
	ds_read_b128 v[160:163], v201 offset:49152
	ds_read_b128 v[164:167], v201 offset:50176
	ds_read_b128 v[188:191], v201 offset:51200
	ds_read_b128 v[192:195], v201 offset:52224
	ds_read_b128 v[202:205], v201 offset:53248
	ds_read_b128 v[206:209], v201 offset:54272
	ds_read_b128 v[210:213], v201 offset:55296
	ds_read_b128 v[214:217], v201 offset:56320
	global_load_lds_dwordx4 v[196:197], off
	s_add_i32 m0, s22, 0x2000
	s_add_u32 s20, s20, 0x100080
	v_lshl_add_u64 v[196:197], v[218:219], 0, s[4:5]
	s_addc_u32 s21, s21, 0
	s_add_i32 s22, s47, s29
	global_load_lds_dwordx4 v[196:197], off
	v_lshl_add_u64 v[196:197], s[20:21], 0, v[170:171]
	s_mov_b32 m0, s22
	s_nop 0
	global_load_lds_dwordx4 v[196:197], off
	v_lshl_add_u64 v[196:197], s[20:21], 0, v[174:175]
	s_add_i32 m0, s22, 0x2000
	s_nop 0
	global_load_lds_dwordx4 v[196:197], off
	v_lshl_add_u64 v[196:197], v[220:221], 0, s[4:5]
	s_mov_b32 m0, s35
	s_nop 0
	global_load_lds_dwordx4 v[196:197], off
	v_lshl_add_u64 v[196:197], v[222:223], 0, s[4:5]
	s_mov_b32 m0, s36
	s_nop 0
	global_load_lds_dwordx4 v[196:197], off
	s_waitcnt vmcnt(8) lgkmcnt(0)
	s_setprio 1
	s_barrier
	v_mfma_f32_16x16x32_bf16 v[60:63], v[128:131], v[160:163], v[60:63]
	v_mfma_f32_16x16x32_bf16 v[56:59], v[136:139], v[160:163], v[56:59]
	v_mfma_f32_16x16x32_bf16 v[48:51], v[128:131], v[188:191], v[48:51]
	v_mfma_f32_16x16x32_bf16 v[40:43], v[136:139], v[188:191], v[40:43]
	v_mfma_f32_16x16x32_bf16 v[32:35], v[128:131], v[202:205], v[32:35]
	v_mfma_f32_16x16x32_bf16 v[24:27], v[136:139], v[202:205], v[24:27]
	v_mfma_f32_16x16x32_bf16 v[16:19], v[128:131], v[210:213], v[16:19]
	v_mfma_f32_16x16x32_bf16 v[8:11], v[136:139], v[210:213], v[8:11]
	v_mfma_f32_16x16x32_bf16 v[60:63], v[132:135], v[164:167], v[60:63]
	v_mfma_f32_16x16x32_bf16 v[56:59], v[140:143], v[164:167], v[56:59]
	v_mfma_f32_16x16x32_bf16 v[48:51], v[132:135], v[192:195], v[48:51]
	v_mfma_f32_16x16x32_bf16 v[40:43], v[140:143], v[192:195], v[40:43]
	v_mfma_f32_16x16x32_bf16 v[32:35], v[132:135], v[206:209], v[32:35]
	v_mfma_f32_16x16x32_bf16 v[24:27], v[140:143], v[206:209], v[24:27]
	v_mfma_f32_16x16x32_bf16 v[16:19], v[132:135], v[214:217], v[16:19]
	v_mfma_f32_16x16x32_bf16 v[8:11], v[140:143], v[214:217], v[8:11]
	v_mfma_f32_16x16x32_bf16 v[52:55], v[144:147], v[160:163], v[52:55]
	v_mfma_f32_16x16x32_bf16 v[44:47], v[152:155], v[160:163], v[44:47]
	v_mfma_f32_16x16x32_bf16 v[36:39], v[144:147], v[188:191], v[36:39]
	v_mfma_f32_16x16x32_bf16 v[28:31], v[152:155], v[188:191], v[28:31]
	v_mfma_f32_16x16x32_bf16 v[20:23], v[144:147], v[202:205], v[20:23]
	v_mfma_f32_16x16x32_bf16 v[12:15], v[152:155], v[202:205], v[12:15]
	v_mfma_f32_16x16x32_bf16 v[4:7], v[144:147], v[210:213], v[4:7]
	v_mfma_f32_16x16x32_bf16 v[0:3], v[152:155], v[210:213], v[0:3]
	v_mfma_f32_16x16x32_bf16 v[52:55], v[148:151], v[164:167], v[52:55]
	v_mfma_f32_16x16x32_bf16 v[44:47], v[156:159], v[164:167], v[44:47]
	v_mfma_f32_16x16x32_bf16 v[36:39], v[148:151], v[192:195], v[36:39]
	v_mfma_f32_16x16x32_bf16 v[28:31], v[156:159], v[192:195], v[28:31]
	v_mfma_f32_16x16x32_bf16 v[20:23], v[148:151], v[206:209], v[20:23]
	v_mfma_f32_16x16x32_bf16 v[12:15], v[156:159], v[206:209], v[12:15]
	v_mfma_f32_16x16x32_bf16 v[4:7], v[148:151], v[214:217], v[4:7]
	v_mfma_f32_16x16x32_bf16 v[0:3], v[156:159], v[214:217], v[0:3]
	s_setprio 0
	s_barrier
	s_add_i32 s45, s45, 2
	s_add_u32 s18, s18, 0x100
	s_addc_u32 s19, s19, 0
	s_add_u32 s43, s43, 0x100
	s_addc_u32 s44, s44, 0
	s_cmp_gt_u32 s45, 61
	s_cbranch_scc0 .LBB0_1061
	s_and_b64 vcc, exec, s[6:7]
	s_cbranch_vccz .LBB0_1064
	s_barrier
